# stack: static priority raise + K-loop loop-edge edit + hgrn pass-0 LDS read hoist on top of v82
# baseline (speedup 1.0000x reference)
; #define PG8_STAGE(bufoff, gbase, voff) do { _Pragma("unroll") for (int _i = 0; _i < 2; ++_i) \
;         __builtin_amdgcn_global_load_lds((const unsigned*)((const char*)(gbase) + (voff)[_i]), (LAS unsigned*)(lds + (bufoff) + ldsw + _i * 8192), 16, 0, 0); } while (0)
; #define PG8_LDA(dst, b, h) do { _Pragma("unroll") for (int m = 0; m < 4; ++m) _Pragma("unroll") for (int k = 0; k < 2; ++k) dst[m][k] = *(const LAS bf16x8*)(lds + PG8_SA(b, h) + aoff + m * 2048 + k * 1024); } while (0)
; #define PG8_LDB(dst, b, h) do { _Pragma("unroll") for (int n = 0; n < 2; ++n) _Pragma("unroll") for (int k = 0; k < 2; ++k) dst[n][k] = *(const LAS bf16x8*)(lds + PG8_SB(b, h) + boff + n * 2048 + k * 1024); } while (0)
; #define PG8_MMA(ai, bj, At, Bt) do { __builtin_amdgcn_s_setprio(1); _Pragma("unroll") for (int m = 0; m < 4; ++m) _Pragma("unroll") for (int n = 0; n < 2; ++n) _Pragma("unroll") for (int k = 0; k < 2; ++k) \
;         acc[ai][bj][m][n] = __builtin_amdgcn_mfma_f32_16x16x32_bf16(Bt[n][k], At[m][k], acc[ai][bj][m][n], 0, 0, 0); __builtin_amdgcn_s_setprio(0); } while (0)
; #define PG8_WAIT_V(n) asm volatile("s_waitcnt vmcnt(" #n ")" ::: "memory")
; #define PG8_WAIT_L(n) asm volatile("s_waitcnt lgkmcnt(" #n ")" ::: "memory")
; #define PG8_BAR __builtin_amdgcn_s_barrier()
; #define PG8_SCHED __builtin_amdgcn_sched_barrier(0)
; template <class Epi>
; __device__ __forceinline__ void gemm_phase(LAS unsigned char* lds, const Gemm g, const int G, const int cidx, const Epi& E) {
;     ...
;         for (int t = 0; t < nt; t += 2) {
;             const bool last = (t == nt - 2);
;             const char* a1 = cA + (size_t)(t + 1) * kstep;
;             const char* a2 = last ? nA : cA + (size_t)(t + 2) * kstep; const char* b2 = last ? nB : cB + (size_t)(t + 2) * kstep;
;             const char* a3 = a2 + kstep; const char* b3 = b2 + kstep;
;             PG8_LDB(B0, 0, 0); PG8_LDB(B1, 0, 1); PG8_SCHED; PG8_LDA(At, 0, 0); PG8_STAGE(PG8_SA(1, 1), a1 + hstep, voffA);
;             PG8_WAIT_V(8); PG8_WAIT_L(0); PG8_BAR; PG8_MMA(0, 0, At, B0); PG8_MMA(0, 1, At, B1); PG8_BAR; PG8_SCHED;
;             PG8_LDA(At, 0, 1); PG8_STAGE(PG8_SB(0, 0), b2, voffB); PG8_STAGE(PG8_SB(0, 1), b2 + hstep, voffB); PG8_STAGE(PG8_SA(0, 0), a2, voffA);
;             PG8_WAIT_V(8); PG8_WAIT_L(0); PG8_BAR; PG8_MMA(1, 0, At, B0); PG8_MMA(1, 1, At, B1); PG8_BAR; PG8_SCHED;
.LBB0_82:
	s_add_i32 s43, 0, 0x10000
	s_add_i32 s68, 0, 0x14000
	v_add_u32_e32 v162, s43, v145
	v_add_u32_e32 v178, s68, v145
	ds_read_b128 v[132:135], v162
	ds_read_b128 v[140:143], v162 offset:1024
	ds_read_b128 v[156:159], v162 offset:2048
	ds_read_b128 v[162:165], v162 offset:3072
	ds_read_b128 v[166:169], v178
	ds_read_b128 v[170:173], v178 offset:1024
	ds_read_b128 v[174:177], v178 offset:2048
	ds_read_b128 v[178:181], v178 offset:3072
	v_lshl_add_u64 v[226:227], s[24:25], 0, v[154:155]
	s_add_i32 m0, s21, 0xc000
	ds_read_b128 v[182:185], v161
	ds_read_b128 v[186:189], v161 offset:1024
	ds_read_b128 v[190:193], v161 offset:2048
	ds_read_b128 v[194:197], v161 offset:3072
	ds_read_b128 v[198:201], v161 offset:4096
	ds_read_b128 v[214:217], v161 offset:5120
	ds_read_b128 v[218:221], v161 offset:6144
	ds_read_b128 v[222:225], v161 offset:7168
	s_add_u32 s26, s24, 0xfffc0080
	s_addc_u32 s27, s25, -1
	s_cmp_eq_u32 s45, 12
	s_cselect_b32 s29, s13, s27
	s_cselect_b32 s28, s17, s26
	s_cselect_b32 s27, s9, s44
	s_cselect_b32 s26, s22, s33
	global_load_lds_dwordx4 v[226:227], off
	v_lshl_add_u64 v[226:227], s[24:25], 0, v[152:153]
	s_add_i32 m0, s21, 0xe000
	s_nop 0
	global_load_lds_dwordx4 v[226:227], off
	s_waitcnt vmcnt(8)
	s_waitcnt lgkmcnt(0)
	s_barrier
	s_waitcnt lgkmcnt(0)
	v_mfma_f32_16x16x32_bf16 v[128:131], v[132:135], v[182:185], v[128:131]
	v_mfma_f32_16x16x32_bf16 v[120:123], v[156:159], v[182:185], v[120:123]
	v_mfma_f32_16x16x32_bf16 v[112:115], v[132:135], v[190:193], v[112:115]
	v_mfma_f32_16x16x32_bf16 v[104:107], v[156:159], v[190:193], v[104:107]
	v_mfma_f32_16x16x32_bf16 v[96:99], v[132:135], v[198:201], v[96:99]
	v_mfma_f32_16x16x32_bf16 v[88:91], v[156:159], v[198:201], v[88:91]
	v_mfma_f32_16x16x32_bf16 v[80:83], v[132:135], v[218:221], v[80:83]
	v_mfma_f32_16x16x32_bf16 v[72:75], v[156:159], v[218:221], v[72:75]
	v_mfma_f32_16x16x32_bf16 v[128:131], v[140:143], v[186:189], v[128:131]
	v_mfma_f32_16x16x32_bf16 v[120:123], v[162:165], v[186:189], v[120:123]
	v_mfma_f32_16x16x32_bf16 v[112:115], v[140:143], v[194:197], v[112:115]
	v_mfma_f32_16x16x32_bf16 v[104:107], v[162:165], v[194:197], v[104:107]
	v_mfma_f32_16x16x32_bf16 v[96:99], v[140:143], v[214:217], v[96:99]
	v_mfma_f32_16x16x32_bf16 v[88:91], v[162:165], v[214:217], v[88:91]
	v_mfma_f32_16x16x32_bf16 v[80:83], v[140:143], v[222:225], v[80:83]
	v_mfma_f32_16x16x32_bf16 v[72:75], v[162:165], v[222:225], v[72:75]
	v_mfma_f32_16x16x32_bf16 v[124:127], v[166:169], v[182:185], v[124:127]
	v_mfma_f32_16x16x32_bf16 v[116:119], v[174:177], v[182:185], v[116:119]
	v_mfma_f32_16x16x32_bf16 v[108:111], v[166:169], v[190:193], v[108:111]
	v_mfma_f32_16x16x32_bf16 v[100:103], v[174:177], v[190:193], v[100:103]
	v_mfma_f32_16x16x32_bf16 v[92:95], v[166:169], v[198:201], v[92:95]
	v_mfma_f32_16x16x32_bf16 v[84:87], v[174:177], v[198:201], v[84:87]
	v_mfma_f32_16x16x32_bf16 v[76:79], v[166:169], v[218:221], v[76:79]
	v_mfma_f32_16x16x32_bf16 v[68:71], v[174:177], v[218:221], v[68:71]
	v_mfma_f32_16x16x32_bf16 v[124:127], v[170:173], v[186:189], v[124:127]
	v_mfma_f32_16x16x32_bf16 v[116:119], v[178:181], v[186:189], v[116:119]
	v_mfma_f32_16x16x32_bf16 v[108:111], v[170:173], v[194:197], v[108:111]
	v_mfma_f32_16x16x32_bf16 v[100:103], v[178:181], v[194:197], v[100:103]
	v_mfma_f32_16x16x32_bf16 v[92:95], v[170:173], v[214:217], v[92:95]
	v_mfma_f32_16x16x32_bf16 v[84:87], v[178:181], v[214:217], v[84:87]
	v_mfma_f32_16x16x32_bf16 v[76:79], v[170:173], v[222:225], v[76:79]
	v_mfma_f32_16x16x32_bf16 v[68:71], v[178:181], v[222:225], v[68:71]
	s_barrier
	s_add_i32 s43, s43, s36
	v_lshl_add_u64 v[226:227], s[26:27], 0, v[148:149]
	s_mov_b32 m0, s43
	ds_read_b128 v[182:185], v161 offset:16384
	ds_read_b128 v[186:189], v161 offset:17408
	ds_read_b128 v[190:193], v161 offset:18432
	ds_read_b128 v[194:197], v161 offset:19456
	ds_read_b128 v[198:201], v161 offset:20480
	ds_read_b128 v[214:217], v161 offset:21504
	ds_read_b128 v[218:221], v161 offset:22528
	ds_read_b128 v[222:225], v161 offset:23552
	global_load_lds_dwordx4 v[226:227], off
	s_add_i32 m0, s43, 0x2000
	s_add_u32 s76, s26, 0x40000
	v_lshl_add_u64 v[228:229], s[26:27], 0, v[0:1]
	s_addc_u32 s77, s27, 0
	s_add_i32 s43, s68, s36
	global_load_lds_dwordx4 v[228:229], off
	v_lshl_add_u64 v[230:231], s[76:77], 0, v[148:149]
	s_mov_b32 m0, s43
	v_lshl_add_u64 v[232:233], s[28:29], 0, v[146:147]
	global_load_lds_dwordx4 v[230:231], off
	v_lshl_add_u64 v[230:231], s[76:77], 0, v[0:1]
	s_add_i32 m0, s43, 0x2000
	s_nop 0
	global_load_lds_dwordx4 v[230:231], off
	v_lshl_add_u64 v[230:231], s[28:29], 0, v[150:151]
	s_mov_b32 m0, s21
	s_nop 0
	global_load_lds_dwordx4 v[230:231], off
	s_mov_b32 m0, s38
	s_nop 0
	global_load_lds_dwordx4 v[232:233], off
	s_waitcnt vmcnt(8)
	s_waitcnt lgkmcnt(0)
	s_barrier
; #define PG8_STAGE(bufoff, gbase, voff) do { _Pragma("unroll") for (int _i = 0; _i < 2; ++_i) \
;         __builtin_amdgcn_global_load_lds((const unsigned*)((const char*)(gbase) + (voff)[_i]), (LAS unsigned*)(lds + (bufoff) + ldsw + _i * 8192), 16, 0, 0); } while (0)
; #define PG8_LDA(dst, b, h) do { _Pragma("unroll") for (int m = 0; m < 4; ++m) _Pragma("unroll") for (int k = 0; k < 2; ++k) dst[m][k] = *(const LAS bf16x8*)(lds + PG8_SA(b, h) + aoff + m * 2048 + k * 1024); } while (0)
; #define PG8_LDB(dst, b, h) do { _Pragma("unroll") for (int n = 0; n < 2; ++n) _Pragma("unroll") for (int k = 0; k < 2; ++k) dst[n][k] = *(const LAS bf16x8*)(lds + PG8_SB(b, h) + boff + n * 2048 + k * 1024); } while (0)
; #define PG8_MMA(ai, bj, At, Bt) do { __builtin_amdgcn_s_setprio(1); _Pragma("unroll") for (int m = 0; m < 4; ++m) _Pragma("unroll") for (int n = 0; n < 2; ++n) _Pragma("unroll") for (int k = 0; k < 2; ++k) \
;         acc[ai][bj][m][n] = __builtin_amdgcn_mfma_f32_16x16x32_bf16(Bt[n][k], At[m][k], acc[ai][bj][m][n], 0, 0, 0); __builtin_amdgcn_s_setprio(0); } while (0)
; #define PG8_WAIT_V(n) asm volatile("s_waitcnt vmcnt(" #n ")" ::: "memory")
; #define PG8_WAIT_L(n) asm volatile("s_waitcnt lgkmcnt(" #n ")" ::: "memory")
; #define PG8_BAR __builtin_amdgcn_s_barrier()
; #define PG8_SCHED __builtin_amdgcn_sched_barrier(0)
; template <class Epi>
; __device__ __forceinline__ void gemm_phase(LAS unsigned char* lds, const Gemm g, const int G, const int cidx, const Epi& E) {
;     ...
;             PG8_WAIT_V(8); PG8_WAIT_L(0); PG8_BAR; PG8_MMA(1, 0, At, B0); PG8_MMA(1, 1, At, B1); PG8_BAR; PG8_SCHED;
;             PG8_LDB(B0, 1, 0); PG8_LDB(B1, 1, 1); PG8_SCHED; PG8_LDA(At, 1, 0); PG8_STAGE(PG8_SA(0, 1), a2 + hstep, voffA);
;             PG8_WAIT_V(8); PG8_WAIT_L(0); PG8_BAR; PG8_MMA(0, 0, At, B0); PG8_MMA(0, 1, At, B1); PG8_BAR; PG8_SCHED;
	s_waitcnt lgkmcnt(0)
	v_mfma_f32_16x16x32_bf16 v[64:67], v[132:135], v[182:185], v[64:67]
	v_mfma_f32_16x16x32_bf16 v[56:59], v[156:159], v[182:185], v[56:59]
	v_mfma_f32_16x16x32_bf16 v[48:51], v[132:135], v[190:193], v[48:51]
	v_mfma_f32_16x16x32_bf16 v[40:43], v[156:159], v[190:193], v[40:43]
	v_mfma_f32_16x16x32_bf16 v[32:35], v[132:135], v[198:201], v[32:35]
	v_mfma_f32_16x16x32_bf16 v[24:27], v[156:159], v[198:201], v[24:27]
	v_mfma_f32_16x16x32_bf16 v[16:19], v[132:135], v[218:221], v[16:19]
	v_mfma_f32_16x16x32_bf16 v[8:11], v[156:159], v[218:221], v[8:11]
	v_mfma_f32_16x16x32_bf16 v[64:67], v[140:143], v[186:189], v[64:67]
	v_mfma_f32_16x16x32_bf16 v[56:59], v[162:165], v[186:189], v[56:59]
	v_mfma_f32_16x16x32_bf16 v[48:51], v[140:143], v[194:197], v[48:51]
	v_mfma_f32_16x16x32_bf16 v[40:43], v[162:165], v[194:197], v[40:43]
	v_mfma_f32_16x16x32_bf16 v[32:35], v[140:143], v[214:217], v[32:35]
	v_mfma_f32_16x16x32_bf16 v[24:27], v[162:165], v[214:217], v[24:27]
	v_mfma_f32_16x16x32_bf16 v[16:19], v[140:143], v[222:225], v[16:19]
	v_mfma_f32_16x16x32_bf16 v[8:11], v[162:165], v[222:225], v[8:11]
	v_mfma_f32_16x16x32_bf16 v[60:63], v[166:169], v[182:185], v[60:63]
	v_mfma_f32_16x16x32_bf16 v[52:55], v[174:177], v[182:185], v[52:55]
	v_mfma_f32_16x16x32_bf16 v[44:47], v[166:169], v[190:193], v[44:47]
	v_mfma_f32_16x16x32_bf16 v[36:39], v[174:177], v[190:193], v[36:39]
	v_mfma_f32_16x16x32_bf16 v[28:31], v[166:169], v[198:201], v[28:31]
	v_mfma_f32_16x16x32_bf16 v[20:23], v[174:177], v[198:201], v[20:23]
	v_mfma_f32_16x16x32_bf16 v[12:15], v[166:169], v[218:221], v[12:15]
	v_mfma_f32_16x16x32_bf16 v[4:7], v[174:177], v[218:221], v[4:7]
	v_mfma_f32_16x16x32_bf16 v[60:63], v[170:173], v[186:189], v[60:63]
	v_mfma_f32_16x16x32_bf16 v[52:55], v[178:181], v[186:189], v[52:55]
	v_mfma_f32_16x16x32_bf16 v[44:47], v[170:173], v[194:197], v[44:47]
	v_mfma_f32_16x16x32_bf16 v[36:39], v[178:181], v[194:197], v[36:39]
	v_mfma_f32_16x16x32_bf16 v[28:31], v[170:173], v[214:217], v[28:31]
	v_mfma_f32_16x16x32_bf16 v[20:23], v[178:181], v[214:217], v[20:23]
	v_mfma_f32_16x16x32_bf16 v[12:15], v[170:173], v[222:225], v[12:15]
	v_mfma_f32_16x16x32_bf16 v[4:7], v[178:181], v[222:225], v[4:7]
	s_barrier
	s_add_i32 s43, 0, 0x18000
	s_add_i32 s68, 0, 0x1c000
	v_add_u32_e32 v162, s43, v145
	v_add_u32_e32 v178, s68, v145
	ds_read_b128 v[132:135], v162
	ds_read_b128 v[140:143], v162 offset:1024
	ds_read_b128 v[156:159], v162 offset:2048
	ds_read_b128 v[162:165], v162 offset:3072
	ds_read_b128 v[166:169], v178
	ds_read_b128 v[170:173], v178 offset:1024
	ds_read_b128 v[174:177], v178 offset:2048
	ds_read_b128 v[178:181], v178 offset:3072
	s_add_u32 s28, s28, 0x40000
	s_addc_u32 s29, s29, 0
	s_mov_b32 m0, s39
	v_lshl_add_u64 v[234:235], s[28:29], 0, v[150:151]
	ds_read_b128 v[182:185], v161 offset:32768
	ds_read_b128 v[186:189], v161 offset:33792
	ds_read_b128 v[190:193], v161 offset:34816
	ds_read_b128 v[194:197], v161 offset:35840
	ds_read_b128 v[198:201], v161 offset:36864
	ds_read_b128 v[214:217], v161 offset:37888
	ds_read_b128 v[218:221], v161 offset:38912
	ds_read_b128 v[222:225], v161 offset:39936
	global_load_lds_dwordx4 v[234:235], off
	v_lshl_add_u64 v[234:235], s[28:29], 0, v[146:147]
	s_mov_b32 m0, s75
	s_nop 0
	global_load_lds_dwordx4 v[234:235], off
	s_waitcnt vmcnt(8)
	s_waitcnt lgkmcnt(0)
	s_barrier
	s_waitcnt lgkmcnt(0)
	v_mfma_f32_16x16x32_bf16 v[128:131], v[132:135], v[182:185], v[128:131]
	v_mfma_f32_16x16x32_bf16 v[120:123], v[156:159], v[182:185], v[120:123]
	v_mfma_f32_16x16x32_bf16 v[112:115], v[132:135], v[190:193], v[112:115]
	v_mfma_f32_16x16x32_bf16 v[104:107], v[156:159], v[190:193], v[104:107]
	v_mfma_f32_16x16x32_bf16 v[96:99], v[132:135], v[198:201], v[96:99]
	v_mfma_f32_16x16x32_bf16 v[88:91], v[156:159], v[198:201], v[88:91]
	v_mfma_f32_16x16x32_bf16 v[80:83], v[132:135], v[218:221], v[80:83]
	v_mfma_f32_16x16x32_bf16 v[72:75], v[156:159], v[218:221], v[72:75]
	v_mfma_f32_16x16x32_bf16 v[128:131], v[140:143], v[186:189], v[128:131]
	v_mfma_f32_16x16x32_bf16 v[120:123], v[162:165], v[186:189], v[120:123]
	v_mfma_f32_16x16x32_bf16 v[112:115], v[140:143], v[194:197], v[112:115]
	v_mfma_f32_16x16x32_bf16 v[104:107], v[162:165], v[194:197], v[104:107]
	v_mfma_f32_16x16x32_bf16 v[96:99], v[140:143], v[214:217], v[96:99]
	v_mfma_f32_16x16x32_bf16 v[88:91], v[162:165], v[214:217], v[88:91]
	v_mfma_f32_16x16x32_bf16 v[80:83], v[140:143], v[222:225], v[80:83]
	v_mfma_f32_16x16x32_bf16 v[72:75], v[162:165], v[222:225], v[72:75]
	v_mfma_f32_16x16x32_bf16 v[124:127], v[166:169], v[182:185], v[124:127]
	v_mfma_f32_16x16x32_bf16 v[116:119], v[174:177], v[182:185], v[116:119]
	v_mfma_f32_16x16x32_bf16 v[108:111], v[166:169], v[190:193], v[108:111]
	v_mfma_f32_16x16x32_bf16 v[100:103], v[174:177], v[190:193], v[100:103]
	v_mfma_f32_16x16x32_bf16 v[92:95], v[166:169], v[198:201], v[92:95]
	v_mfma_f32_16x16x32_bf16 v[84:87], v[174:177], v[198:201], v[84:87]
	v_mfma_f32_16x16x32_bf16 v[76:79], v[166:169], v[218:221], v[76:79]
	v_mfma_f32_16x16x32_bf16 v[68:71], v[174:177], v[218:221], v[68:71]
	v_mfma_f32_16x16x32_bf16 v[124:127], v[170:173], v[186:189], v[124:127]
	v_mfma_f32_16x16x32_bf16 v[116:119], v[178:181], v[186:189], v[116:119]
	v_mfma_f32_16x16x32_bf16 v[108:111], v[170:173], v[194:197], v[108:111]
	v_mfma_f32_16x16x32_bf16 v[100:103], v[178:181], v[194:197], v[100:103]
	v_mfma_f32_16x16x32_bf16 v[92:95], v[170:173], v[214:217], v[92:95]
	v_mfma_f32_16x16x32_bf16 v[84:87], v[178:181], v[214:217], v[84:87]
	v_mfma_f32_16x16x32_bf16 v[76:79], v[170:173], v[222:225], v[76:79]
	v_mfma_f32_16x16x32_bf16 v[68:71], v[178:181], v[222:225], v[68:71]
	s_barrier
; __device__ __forceinline__ unsigned pk2(float lo, float hi) { unsigned r; asm("v_cvt_pk_bf16_f32 %0, %1, %2" : "=v"(r) : "v"(lo), "v"(hi)); return r; }
; __device__ __forceinline__ float silu(float x) { return x * sigm(x); }
; #define PG8_STAGE(bufoff, gbase, voff) do { _Pragma("unroll") for (int _i = 0; _i < 2; ++_i) \
;         __builtin_amdgcn_global_load_lds((const unsigned*)((const char*)(gbase) + (voff)[_i]), (LAS unsigned*)(lds + (bufoff) + ldsw + _i * 8192), 16, 0, 0); } while (0)
; #define PG8_LDA(dst, b, h) do { _Pragma("unroll") for (int m = 0; m < 4; ++m) _Pragma("unroll") for (int k = 0; k < 2; ++k) dst[m][k] = *(const LAS bf16x8*)(lds + PG8_SA(b, h) + aoff + m * 2048 + k * 1024); } while (0)
; #define PG8_MMA(ai, bj, At, Bt) do { __builtin_amdgcn_s_setprio(1); _Pragma("unroll") for (int m = 0; m < 4; ++m) _Pragma("unroll") for (int n = 0; n < 2; ++n) _Pragma("unroll") for (int k = 0; k < 2; ++k) \
;         acc[ai][bj][m][n] = __builtin_amdgcn_mfma_f32_16x16x32_bf16(Bt[n][k], At[m][k], acc[ai][bj][m][n], 0, 0, 0); __builtin_amdgcn_s_setprio(0); } while (0)
;     __device__ __forceinline__ void operator()(const f32x4 (&acc)[2][2][4][2], const Unit& u, int wr, int wc, int fr, int fq) const {
;         const int row0 = u.pm * BM + wr * 64 + fr, col0 = u.pn * HALF + wc * 32 + 8 * fq;
; #pragma unroll
;         for (int ai = 0; ai < 2; ++ai)
; #pragma unroll
;             for (int m = 0; m < 4; ++m) { bf16_t* rowp = O + (size_t)(row0 + ai * HALF + m * 16) * ldc + col0;
;                 const f32x4 g0 = acc[ai][0][m][0], g1 = acc[ai][0][m][1], u0 = acc[ai][1][m][0], u1 = acc[ai][1][m][1];
;                 u32x4 w; w.x = pk2(silu(g0[0]) * u0[0], silu(g0[1]) * u0[1]); w.y = pk2(silu(g0[2]) * u0[2], silu(g0[3]) * u0[3]);
;                 w.z = pk2(silu(g1[0]) * u1[0], silu(g1[1]) * u1[1]); w.w = pk2(silu(g1[2]) * u1[2], silu(g1[3]) * u1[3]);
;                 *(u32x4*)rowp = w; }
; template <class Epi>
; __device__ __forceinline__ void gemm_phase(LAS unsigned char* lds, const Gemm g, const int G, const int cidx, const Epi& E) {
;     ...
;             PG8_LDA(At, 1, 1); PG8_STAGE(PG8_SB(1, 0), b3, voffB); PG8_STAGE(PG8_SB(1, 1), b3 + hstep, voffB); PG8_STAGE(PG8_SA(1, 0), a3, voffA);
;             PG8_WAIT_V(8); PG8_WAIT_L(0); PG8_BAR; PG8_MMA(1, 0, At, B0); PG8_MMA(1, 1, At, B1); PG8_BAR; PG8_SCHED;
;         }
	s_add_i32 s28, s43, s36
	v_lshl_add_u64 v[226:227], v[226:227], 0, s[46:47]
	s_mov_b32 m0, s28
	ds_read_b128 v[182:185], v161 offset:49152
	ds_read_b128 v[186:189], v161 offset:50176
	ds_read_b128 v[190:193], v161 offset:51200
	ds_read_b128 v[194:197], v161 offset:52224
	ds_read_b128 v[198:201], v161 offset:53248
	ds_read_b128 v[214:217], v161 offset:54272
	ds_read_b128 v[218:221], v161 offset:55296
	ds_read_b128 v[222:225], v161 offset:56320
	global_load_lds_dwordx4 v[226:227], off
	s_add_i32 m0, s28, 0x2000
	s_add_u32 s26, s26, 0x40080
	v_lshl_add_u64 v[226:227], v[228:229], 0, s[46:47]
	s_addc_u32 s27, s27, 0
	s_add_i32 s28, s68, s36
	global_load_lds_dwordx4 v[226:227], off
	v_lshl_add_u64 v[226:227], s[26:27], 0, v[148:149]
	s_mov_b32 m0, s28
	s_nop 0
	global_load_lds_dwordx4 v[226:227], off
	v_lshl_add_u64 v[226:227], s[26:27], 0, v[0:1]
	s_add_i32 m0, s28, 0x2000
	s_nop 0
	global_load_lds_dwordx4 v[226:227], off
	v_lshl_add_u64 v[226:227], v[230:231], 0, s[46:47]
	s_mov_b32 m0, s79
	s_nop 0
	global_load_lds_dwordx4 v[226:227], off
	v_lshl_add_u64 v[226:227], v[232:233], 0, s[46:47]
	s_mov_b32 m0, s34
	s_nop 0
	global_load_lds_dwordx4 v[226:227], off
	s_waitcnt vmcnt(8)
	s_waitcnt lgkmcnt(0)
	s_barrier
	s_waitcnt lgkmcnt(0)
	v_mfma_f32_16x16x32_bf16 v[64:67], v[132:135], v[182:185], v[64:67]
	v_mfma_f32_16x16x32_bf16 v[56:59], v[156:159], v[182:185], v[56:59]
	v_mfma_f32_16x16x32_bf16 v[48:51], v[132:135], v[190:193], v[48:51]
	v_mfma_f32_16x16x32_bf16 v[40:43], v[156:159], v[190:193], v[40:43]
	v_mfma_f32_16x16x32_bf16 v[32:35], v[132:135], v[198:201], v[32:35]
	v_mfma_f32_16x16x32_bf16 v[24:27], v[156:159], v[198:201], v[24:27]
	v_mfma_f32_16x16x32_bf16 v[16:19], v[132:135], v[218:221], v[16:19]
	v_mfma_f32_16x16x32_bf16 v[8:11], v[156:159], v[218:221], v[8:11]
	v_mfma_f32_16x16x32_bf16 v[64:67], v[140:143], v[186:189], v[64:67]
	v_mfma_f32_16x16x32_bf16 v[56:59], v[162:165], v[186:189], v[56:59]
	v_mfma_f32_16x16x32_bf16 v[48:51], v[140:143], v[194:197], v[48:51]
	v_mfma_f32_16x16x32_bf16 v[40:43], v[162:165], v[194:197], v[40:43]
	v_mfma_f32_16x16x32_bf16 v[32:35], v[140:143], v[214:217], v[32:35]
	v_mfma_f32_16x16x32_bf16 v[24:27], v[162:165], v[214:217], v[24:27]
	v_mfma_f32_16x16x32_bf16 v[16:19], v[140:143], v[222:225], v[16:19]
	v_mfma_f32_16x16x32_bf16 v[8:11], v[162:165], v[222:225], v[8:11]
	v_mfma_f32_16x16x32_bf16 v[60:63], v[166:169], v[182:185], v[60:63]
	v_mfma_f32_16x16x32_bf16 v[52:55], v[174:177], v[182:185], v[52:55]
	v_mfma_f32_16x16x32_bf16 v[44:47], v[166:169], v[190:193], v[44:47]
	v_mfma_f32_16x16x32_bf16 v[36:39], v[174:177], v[190:193], v[36:39]
	v_mfma_f32_16x16x32_bf16 v[28:31], v[166:169], v[198:201], v[28:31]
	v_mfma_f32_16x16x32_bf16 v[20:23], v[174:177], v[198:201], v[20:23]
	v_mfma_f32_16x16x32_bf16 v[12:15], v[166:169], v[218:221], v[12:15]
	v_mfma_f32_16x16x32_bf16 v[4:7], v[174:177], v[218:221], v[4:7]
	v_mfma_f32_16x16x32_bf16 v[60:63], v[170:173], v[186:189], v[60:63]
	v_mfma_f32_16x16x32_bf16 v[52:55], v[178:181], v[186:189], v[52:55]
	v_mfma_f32_16x16x32_bf16 v[44:47], v[170:173], v[194:197], v[44:47]
	v_mfma_f32_16x16x32_bf16 v[36:39], v[178:181], v[194:197], v[36:39]
	v_mfma_f32_16x16x32_bf16 v[28:31], v[170:173], v[214:217], v[28:31]
	v_mfma_f32_16x16x32_bf16 v[20:23], v[178:181], v[214:217], v[20:23]
	v_mfma_f32_16x16x32_bf16 v[12:15], v[170:173], v[222:225], v[12:15]
	v_mfma_f32_16x16x32_bf16 v[4:7], v[178:181], v[222:225], v[4:7]
	s_add_i32 s45, s45, 2
	s_add_u32 s33, s33, 0x100
	s_addc_u32 s44, s44, 0
	s_add_u32 s24, s24, 0x100
	s_addc_u32 s25, s25, 0
	s_cmp_gt_u32 s45, 13
	s_barrier
	s_cbranch_scc0 .LBB0_82
	v_lshl_or_b32 v132, s16, 7, v160
	v_lshl_add_u32 v162, s20, 8, v3
	v_ashrrev_i32_e32 v133, 31, v132
	v_mov_b64_e32 v[156:157], s[6:7]
	s_movk_i32 s9, 0x1600
	v_mad_i64_i32 v[134:135], s[16:17], v162, s9, v[156:157]
	v_lshlrev_b64 v[158:159], 1, v[132:133]
	v_lshl_add_u64 v[132:133], v[134:135], 0, v[158:159]
	v_mul_f32_e32 v134, 0xbfb8aa3b, v128
	v_exp_f32_e32 v134, v134
	s_and_b64 vcc, exec, s[4:5]
	s_mov_b32 s20, s12
	s_mov_b64 s[24:25], s[18:19]
	v_add_f32_e32 v134, 1.0, v134
	v_rcp_f32_e32 v134, v134
	s_mov_b64 s[26:27], s[14:15]
	v_mul_f32_e32 v128, v128, v134
	v_mul_f32_e32 v124, v128, v124
	v_mul_f32_e32 v128, 0xbfb8aa3b, v129
	v_exp_f32_e32 v128, v128
	s_nop 0
	v_add_f32_e32 v128, 1.0, v128
	v_rcp_f32_e32 v128, v128
	s_nop 0
	v_mul_f32_e32 v128, v129, v128
	v_mul_f32_e32 v125, v128, v125
	v_cvt_pk_bf16_f32 v124, v124, v125
	v_mul_f32_e32 v125, 0xbfb8aa3b, v130
	v_exp_f32_e32 v125, v125
	s_nop 0
	v_add_f32_e32 v125, 1.0, v125
	v_rcp_f32_e32 v125, v125
	s_nop 0
	v_mul_f32_e32 v125, v130, v125
	v_mul_f32_e32 v125, v125, v126
	v_mul_f32_e32 v126, 0xbfb8aa3b, v131
	v_exp_f32_e32 v126, v126
	s_nop 0
	v_add_f32_e32 v126, 1.0, v126
	v_rcp_f32_e32 v126, v126
	s_nop 0
	v_mul_f32_e32 v126, v131, v126
	v_mul_f32_e32 v126, v126, v127
	v_cvt_pk_bf16_f32 v125, v125, v126
	v_mul_f32_e32 v126, 0xbfb8aa3b, v120
	v_exp_f32_e32 v126, v126
	s_nop 0
	v_add_f32_e32 v126, 1.0, v126
	v_rcp_f32_e32 v126, v126
	s_nop 0
	v_mul_f32_e32 v120, v120, v126
	v_mul_f32_e32 v116, v120, v116
	v_mul_f32_e32 v120, 0xbfb8aa3b, v121
	v_exp_f32_e32 v120, v120
	s_nop 0
	v_add_f32_e32 v120, 1.0, v120
	v_rcp_f32_e32 v120, v120
	s_nop 0
	v_mul_f32_e32 v120, v121, v120
	v_mul_f32_e32 v117, v120, v117
	v_cvt_pk_bf16_f32 v126, v116, v117
	v_mul_f32_e32 v116, 0xbfb8aa3b, v122
	v_exp_f32_e32 v116, v116
	v_mul_f32_e32 v117, 0xbfb8aa3b, v123
	v_exp_f32_e32 v117, v117
	v_add_f32_e32 v116, 1.0, v116
	v_rcp_f32_e32 v116, v116
	v_add_f32_e32 v117, 1.0, v117
	v_rcp_f32_e32 v117, v117
	v_mul_f32_e32 v116, v122, v116
; __device__ __forceinline__ unsigned pk2(float lo, float hi) { unsigned r; asm("v_cvt_pk_bf16_f32 %0, %1, %2" : "=v"(r) : "v"(lo), "v"(hi)); return r; }
; __device__ __forceinline__ float silu(float x) { return x * sigm(x); }
;     __device__ __forceinline__ void operator()(const f32x4 (&acc)[2][2][4][2], const Unit& u, int wr, int wc, int fr, int fq) const {
;         const int row0 = u.pm * BM + wr * 64 + fr, col0 = u.pn * HALF + wc * 32 + 8 * fq;
; #pragma unroll
;         for (int ai = 0; ai < 2; ++ai)
; #pragma unroll
;             for (int m = 0; m < 4; ++m) { bf16_t* rowp = O + (size_t)(row0 + ai * HALF + m * 16) * ldc + col0;
;                 const f32x4 g0 = acc[ai][0][m][0], g1 = acc[ai][0][m][1], u0 = acc[ai][1][m][0], u1 = acc[ai][1][m][1];
;                 u32x4 w; w.x = pk2(silu(g0[0]) * u0[0], silu(g0[1]) * u0[1]); w.y = pk2(silu(g0[2]) * u0[2], silu(g0[3]) * u0[3]);
;                 w.z = pk2(silu(g1[0]) * u1[0], silu(g1[1]) * u1[1]); w.w = pk2(silu(g1[2]) * u1[2], silu(g1[3]) * u1[3]);
;                 *(u32x4*)rowp = w; }
	v_mul_f32_e32 v116, v116, v118
	v_mul_f32_e32 v118, 0xbfb8aa3b, v112
	v_exp_f32_e32 v118, v118
	v_mul_f32_e32 v117, v123, v117
	v_mul_f32_e32 v117, v117, v119
	v_cvt_pk_bf16_f32 v127, v116, v117
	v_add_f32_e32 v118, 1.0, v118
	v_rcp_f32_e32 v118, v118
	s_mov_b64 s[98:99], 0x16000
	v_mul_f32_e32 v112, v112, v118
	v_mul_f32_e32 v108, v112, v108
	v_mul_f32_e32 v112, 0xbfb8aa3b, v113
	v_exp_f32_e32 v112, v112
	v_lshl_add_u64 v[116:117], v[132:133], 0, s[98:99]
	global_store_dwordx4 v[132:133], v[124:127], off
	v_add_f32_e32 v112, 1.0, v112
	v_rcp_f32_e32 v112, v112
	s_nop 0
	v_mul_f32_e32 v112, v113, v112
	v_mul_f32_e32 v109, v112, v109
	v_cvt_pk_bf16_f32 v108, v108, v109
	v_mul_f32_e32 v109, 0xbfb8aa3b, v114
	v_exp_f32_e32 v109, v109
	s_nop 0
	v_add_f32_e32 v109, 1.0, v109
	v_rcp_f32_e32 v109, v109
	s_nop 0
	v_mul_f32_e32 v109, v114, v109
	v_mul_f32_e32 v109, v109, v110
	v_mul_f32_e32 v110, 0xbfb8aa3b, v115
	v_exp_f32_e32 v110, v110
	s_nop 0
	v_add_f32_e32 v110, 1.0, v110
	v_rcp_f32_e32 v110, v110
	s_nop 0
	v_mul_f32_e32 v110, v115, v110
	v_mul_f32_e32 v110, v110, v111
	v_cvt_pk_bf16_f32 v109, v109, v110
	v_mul_f32_e32 v110, 0xbfb8aa3b, v104
	v_exp_f32_e32 v110, v110
	s_nop 0
	v_add_f32_e32 v110, 1.0, v110
	v_rcp_f32_e32 v110, v110
	s_nop 0
	v_mul_f32_e32 v104, v104, v110
	v_mul_f32_e32 v100, v104, v100
	v_mul_f32_e32 v104, 0xbfb8aa3b, v105
	v_exp_f32_e32 v104, v104
	s_nop 0
	v_add_f32_e32 v104, 1.0, v104
	v_rcp_f32_e32 v104, v104
	s_nop 0
	v_mul_f32_e32 v104, v105, v104
	v_mul_f32_e32 v101, v104, v101
	v_cvt_pk_bf16_f32 v110, v100, v101
	v_mul_f32_e32 v100, 0xbfb8aa3b, v106
	v_exp_f32_e32 v100, v100
	v_mul_f32_e32 v101, 0xbfb8aa3b, v107
	v_exp_f32_e32 v101, v101
	v_add_f32_e32 v100, 1.0, v100
	v_rcp_f32_e32 v100, v100
	v_add_f32_e32 v101, 1.0, v101
	v_rcp_f32_e32 v101, v101
	v_mul_f32_e32 v100, v106, v100
	v_mul_f32_e32 v100, v100, v102
	v_mul_f32_e32 v102, 0xbfb8aa3b, v96
	v_exp_f32_e32 v102, v102
	v_mul_f32_e32 v101, v107, v101
	v_mul_f32_e32 v101, v101, v103
	v_cvt_pk_bf16_f32 v111, v100, v101
	v_add_f32_e32 v102, 1.0, v102
	v_rcp_f32_e32 v102, v102
	s_mov_b64 s[98:99], 0x2c000
	v_mul_f32_e32 v96, v96, v102
	v_mul_f32_e32 v92, v96, v92
	v_mul_f32_e32 v96, 0xbfb8aa3b, v97
	v_exp_f32_e32 v96, v96
	v_lshl_add_u64 v[100:101], v[132:133], 0, s[98:99]
	global_store_dwordx4 v[116:117], v[108:111], off
	v_add_f32_e32 v96, 1.0, v96
	v_rcp_f32_e32 v96, v96
	s_nop 0
	v_mul_f32_e32 v96, v97, v96
	v_mul_f32_e32 v93, v96, v93
	v_cvt_pk_bf16_f32 v92, v92, v93
	v_mul_f32_e32 v93, 0xbfb8aa3b, v98
	v_exp_f32_e32 v93, v93
	s_nop 0
	v_add_f32_e32 v93, 1.0, v93
	v_rcp_f32_e32 v93, v93
	s_nop 0
	v_mul_f32_e32 v93, v98, v93
	v_mul_f32_e32 v93, v93, v94
	v_mul_f32_e32 v94, 0xbfb8aa3b, v99
	v_exp_f32_e32 v94, v94
	s_nop 0
	v_add_f32_e32 v94, 1.0, v94
	v_rcp_f32_e32 v94, v94
	s_nop 0
	v_mul_f32_e32 v94, v99, v94
	v_mul_f32_e32 v94, v94, v95
	v_cvt_pk_bf16_f32 v93, v93, v94
	v_mul_f32_e32 v94, 0xbfb8aa3b, v88
	v_exp_f32_e32 v94, v94
	s_nop 0
	v_add_f32_e32 v94, 1.0, v94
	v_rcp_f32_e32 v94, v94
	s_nop 0
	v_mul_f32_e32 v88, v88, v94
	v_mul_f32_e32 v84, v88, v84
	v_mul_f32_e32 v88, 0xbfb8aa3b, v89
	v_exp_f32_e32 v88, v88
	s_nop 0
	v_add_f32_e32 v88, 1.0, v88
	v_rcp_f32_e32 v88, v88
	s_nop 0
	v_mul_f32_e32 v88, v89, v88
	v_mul_f32_e32 v85, v88, v85
	v_cvt_pk_bf16_f32 v94, v84, v85
	v_mul_f32_e32 v84, 0xbfb8aa3b, v90
	v_exp_f32_e32 v84, v84
	v_mul_f32_e32 v85, 0xbfb8aa3b, v91
	v_exp_f32_e32 v85, v85
	v_add_f32_e32 v84, 1.0, v84
	v_rcp_f32_e32 v84, v84
	v_add_f32_e32 v85, 1.0, v85
	v_rcp_f32_e32 v85, v85
	v_mul_f32_e32 v84, v90, v84
	v_mul_f32_e32 v84, v84, v86
	v_mul_f32_e32 v86, 0xbfb8aa3b, v80
	v_exp_f32_e32 v86, v86
	v_mul_f32_e32 v85, v91, v85
	v_mul_f32_e32 v85, v85, v87
	v_cvt_pk_bf16_f32 v95, v84, v85
	v_add_f32_e32 v86, 1.0, v86
	v_rcp_f32_e32 v86, v86
	s_mov_b64 s[98:99], 0x42000
	v_mul_f32_e32 v80, v80, v86
	v_mul_f32_e32 v76, v80, v76
	v_mul_f32_e32 v80, 0xbfb8aa3b, v81
	v_exp_f32_e32 v80, v80
	v_lshl_add_u64 v[84:85], v[132:133], 0, s[98:99]
	global_store_dwordx4 v[100:101], v[92:95], off
	v_add_f32_e32 v80, 1.0, v80
	v_rcp_f32_e32 v80, v80
	s_nop 0
	v_mul_f32_e32 v80, v81, v80
	v_mul_f32_e32 v77, v80, v77
	v_cvt_pk_bf16_f32 v76, v76, v77
	v_mul_f32_e32 v77, 0xbfb8aa3b, v82
	v_exp_f32_e32 v77, v77
	s_nop 0
	v_add_f32_e32 v77, 1.0, v77
	v_rcp_f32_e32 v77, v77
	s_nop 0
	v_mul_f32_e32 v77, v82, v77
	v_mul_f32_e32 v77, v77, v78
	v_mul_f32_e32 v78, 0xbfb8aa3b, v83
	v_exp_f32_e32 v78, v78
	s_nop 0
	v_add_f32_e32 v78, 1.0, v78
	v_rcp_f32_e32 v78, v78
	s_nop 0
	v_mul_f32_e32 v78, v83, v78
	v_mul_f32_e32 v78, v78, v79
	v_cvt_pk_bf16_f32 v77, v77, v78
	v_mul_f32_e32 v78, 0xbfb8aa3b, v72
	v_exp_f32_e32 v78, v78
	s_nop 0
	v_add_f32_e32 v78, 1.0, v78
	v_rcp_f32_e32 v78, v78
	s_nop 0
	v_mul_f32_e32 v72, v72, v78
	v_mul_f32_e32 v68, v72, v68
	v_mul_f32_e32 v72, 0xbfb8aa3b, v73
	v_exp_f32_e32 v72, v72
	s_nop 0
	v_add_f32_e32 v72, 1.0, v72
	v_rcp_f32_e32 v72, v72
	s_nop 0
	v_mul_f32_e32 v72, v73, v72
	v_mul_f32_e32 v69, v72, v69
	v_cvt_pk_bf16_f32 v78, v68, v69
	v_mul_f32_e32 v68, 0xbfb8aa3b, v74
	v_exp_f32_e32 v68, v68
	v_mul_f32_e32 v69, 0xbfb8aa3b, v75
	v_exp_f32_e32 v69, v69
	v_add_f32_e32 v68, 1.0, v68
	v_rcp_f32_e32 v68, v68
	v_add_f32_e32 v69, 1.0, v69
	v_rcp_f32_e32 v69, v69
	v_mul_f32_e32 v68, v74, v68
	v_mul_f32_e32 v68, v68, v70
	v_mul_f32_e32 v70, 0xbfb8aa3b, v64
	v_exp_f32_e32 v70, v70
	v_mul_f32_e32 v69, v75, v69
	v_mul_f32_e32 v69, v69, v71
	v_cvt_pk_bf16_f32 v79, v68, v69
	v_add_f32_e32 v70, 1.0, v70
	v_rcp_f32_e32 v70, v70
	s_mov_b64 s[98:99], 0xb0000
	v_mul_f32_e32 v64, v64, v70
	v_mul_f32_e32 v60, v64, v60
	v_mul_f32_e32 v64, 0xbfb8aa3b, v65
; __device__ __forceinline__ unsigned pk2(float lo, float hi) { unsigned r; asm("v_cvt_pk_bf16_f32 %0, %1, %2" : "=v"(r) : "v"(lo), "v"(hi)); return r; }
; __device__ __forceinline__ float silu(float x) { return x * sigm(x); }
; #define PG8_WAIT_V(n) asm volatile("s_waitcnt vmcnt(" #n ")" ::: "memory")
; #define PG8_BAR __builtin_amdgcn_s_barrier()
;     __device__ __forceinline__ void operator()(const f32x4 (&acc)[2][2][4][2], const Unit& u, int wr, int wc, int fr, int fq) const {
;         const int row0 = u.pm * BM + wr * 64 + fr, col0 = u.pn * HALF + wc * 32 + 8 * fq;
; #pragma unroll
;         for (int ai = 0; ai < 2; ++ai)
; #pragma unroll
;             for (int m = 0; m < 4; ++m) { bf16_t* rowp = O + (size_t)(row0 + ai * HALF + m * 16) * ldc + col0;
;                 const f32x4 g0 = acc[ai][0][m][0], g1 = acc[ai][0][m][1], u0 = acc[ai][1][m][0], u1 = acc[ai][1][m][1];
;                 u32x4 w; w.x = pk2(silu(g0[0]) * u0[0], silu(g0[1]) * u0[1]); w.y = pk2(silu(g0[2]) * u0[2], silu(g0[3]) * u0[3]);
;                 w.z = pk2(silu(g1[0]) * u1[0], silu(g1[1]) * u1[1]); w.w = pk2(silu(g1[2]) * u1[2], silu(g1[3]) * u1[3]);
;                 *(u32x4*)rowp = w; }
; template <class Epi>
; __device__ __forceinline__ void gemm_phase(LAS unsigned char* lds, const Gemm g, const int G, const int cidx, const Epi& E) {
;     ...
;     }
;     PG8_WAIT_V(0);
;     if (wr == 0) PG8_BAR;
	v_exp_f32_e32 v64, v64
	v_lshl_add_u64 v[68:69], v[132:133], 0, s[98:99]
	global_store_dwordx4 v[84:85], v[76:79], off
	v_add_f32_e32 v64, 1.0, v64
	v_rcp_f32_e32 v64, v64
	s_nop 0
	v_mul_f32_e32 v64, v65, v64
	v_mul_f32_e32 v61, v64, v61
	v_cvt_pk_bf16_f32 v60, v60, v61
	v_mul_f32_e32 v61, 0xbfb8aa3b, v66
	v_exp_f32_e32 v61, v61
	s_nop 0
	v_add_f32_e32 v61, 1.0, v61
	v_rcp_f32_e32 v61, v61
	s_nop 0
	v_mul_f32_e32 v61, v66, v61
	v_mul_f32_e32 v61, v61, v62
	v_mul_f32_e32 v62, 0xbfb8aa3b, v67
	v_exp_f32_e32 v62, v62
	s_nop 0
	v_add_f32_e32 v62, 1.0, v62
	v_rcp_f32_e32 v62, v62
	s_nop 0
	v_mul_f32_e32 v62, v67, v62
	v_mul_f32_e32 v62, v62, v63
	v_cvt_pk_bf16_f32 v61, v61, v62
	v_mul_f32_e32 v62, 0xbfb8aa3b, v56
	v_exp_f32_e32 v62, v62
	s_nop 0
	v_add_f32_e32 v62, 1.0, v62
	v_rcp_f32_e32 v62, v62
	s_nop 0
	v_mul_f32_e32 v56, v56, v62
	v_mul_f32_e32 v52, v56, v52
	v_mul_f32_e32 v56, 0xbfb8aa3b, v57
	v_exp_f32_e32 v56, v56
	s_nop 0
	v_add_f32_e32 v56, 1.0, v56
	v_rcp_f32_e32 v56, v56
	s_nop 0
	v_mul_f32_e32 v56, v57, v56
	v_mul_f32_e32 v53, v56, v53
	v_cvt_pk_bf16_f32 v62, v52, v53
	v_mul_f32_e32 v52, 0xbfb8aa3b, v58
	v_exp_f32_e32 v52, v52
	v_mul_f32_e32 v53, 0xbfb8aa3b, v59
	v_exp_f32_e32 v53, v53
	v_add_f32_e32 v52, 1.0, v52
	v_rcp_f32_e32 v52, v52
	v_add_f32_e32 v53, 1.0, v53
	v_rcp_f32_e32 v53, v53
	v_mul_f32_e32 v52, v58, v52
	v_mul_f32_e32 v52, v52, v54
	v_mul_f32_e32 v54, 0xbfb8aa3b, v48
	v_exp_f32_e32 v54, v54
	v_mul_f32_e32 v53, v59, v53
	v_mul_f32_e32 v53, v53, v55
	v_cvt_pk_bf16_f32 v63, v52, v53
	v_add_f32_e32 v54, 1.0, v54
	v_rcp_f32_e32 v54, v54
	s_mov_b64 s[98:99], 0xc6000
	v_mul_f32_e32 v48, v48, v54
	v_mul_f32_e32 v44, v48, v44
	v_mul_f32_e32 v48, 0xbfb8aa3b, v49
	v_exp_f32_e32 v48, v48
	v_lshl_add_u64 v[52:53], v[132:133], 0, s[98:99]
	global_store_dwordx4 v[68:69], v[60:63], off
	v_add_f32_e32 v48, 1.0, v48
	v_rcp_f32_e32 v48, v48
	s_nop 0
	v_mul_f32_e32 v48, v49, v48
	v_mul_f32_e32 v45, v48, v45
	v_cvt_pk_bf16_f32 v44, v44, v45
	v_mul_f32_e32 v45, 0xbfb8aa3b, v50
	v_exp_f32_e32 v45, v45
	s_nop 0
	v_add_f32_e32 v45, 1.0, v45
	v_rcp_f32_e32 v45, v45
	s_nop 0
	v_mul_f32_e32 v45, v50, v45
	v_mul_f32_e32 v45, v45, v46
	v_mul_f32_e32 v46, 0xbfb8aa3b, v51
	v_exp_f32_e32 v46, v46
	s_nop 0
	v_add_f32_e32 v46, 1.0, v46
	v_rcp_f32_e32 v46, v46
	s_nop 0
	v_mul_f32_e32 v46, v51, v46
	v_mul_f32_e32 v46, v46, v47
	v_cvt_pk_bf16_f32 v45, v45, v46
	v_mul_f32_e32 v46, 0xbfb8aa3b, v40
	v_exp_f32_e32 v46, v46
	s_nop 0
	v_add_f32_e32 v46, 1.0, v46
	v_rcp_f32_e32 v46, v46
	s_nop 0
	v_mul_f32_e32 v40, v40, v46
	v_mul_f32_e32 v36, v40, v36
	v_mul_f32_e32 v40, 0xbfb8aa3b, v41
	v_exp_f32_e32 v40, v40
	s_nop 0
	v_add_f32_e32 v40, 1.0, v40
	v_rcp_f32_e32 v40, v40
	s_nop 0
	v_mul_f32_e32 v40, v41, v40
	v_mul_f32_e32 v37, v40, v37
	v_cvt_pk_bf16_f32 v46, v36, v37
	v_mul_f32_e32 v36, 0xbfb8aa3b, v42
	v_exp_f32_e32 v36, v36
	v_mul_f32_e32 v37, 0xbfb8aa3b, v43
	v_exp_f32_e32 v37, v37
	v_add_f32_e32 v36, 1.0, v36
	v_rcp_f32_e32 v36, v36
	v_add_f32_e32 v37, 1.0, v37
	v_rcp_f32_e32 v37, v37
	v_mul_f32_e32 v36, v42, v36
	v_mul_f32_e32 v36, v36, v38
	v_mul_f32_e32 v38, 0xbfb8aa3b, v32
	v_exp_f32_e32 v38, v38
	v_mul_f32_e32 v37, v43, v37
	v_mul_f32_e32 v37, v37, v39
	v_cvt_pk_bf16_f32 v47, v36, v37
	v_add_f32_e32 v38, 1.0, v38
	v_rcp_f32_e32 v38, v38
	s_mov_b64 s[98:99], 0xdc000
	v_mul_f32_e32 v32, v32, v38
	v_mul_f32_e32 v28, v32, v28
	v_mul_f32_e32 v32, 0xbfb8aa3b, v33
	v_exp_f32_e32 v32, v32
	v_lshl_add_u64 v[36:37], v[132:133], 0, s[98:99]
	global_store_dwordx4 v[52:53], v[44:47], off
	v_add_f32_e32 v32, 1.0, v32
	v_rcp_f32_e32 v32, v32
	s_nop 0
	v_mul_f32_e32 v32, v33, v32
	v_mul_f32_e32 v29, v32, v29
	v_cvt_pk_bf16_f32 v28, v28, v29
	v_mul_f32_e32 v29, 0xbfb8aa3b, v34
	v_exp_f32_e32 v29, v29
	s_nop 0
	v_add_f32_e32 v29, 1.0, v29
	v_rcp_f32_e32 v29, v29
	s_nop 0
	v_mul_f32_e32 v29, v34, v29
	v_mul_f32_e32 v29, v29, v30
	v_mul_f32_e32 v30, 0xbfb8aa3b, v35
	v_exp_f32_e32 v30, v30
	s_nop 0
	v_add_f32_e32 v30, 1.0, v30
	v_rcp_f32_e32 v30, v30
	s_nop 0
	v_mul_f32_e32 v30, v35, v30
	v_mul_f32_e32 v30, v30, v31
	v_cvt_pk_bf16_f32 v29, v29, v30
	v_mul_f32_e32 v30, 0xbfb8aa3b, v24
	v_exp_f32_e32 v30, v30
	s_nop 0
	v_add_f32_e32 v30, 1.0, v30
	v_rcp_f32_e32 v30, v30
	s_nop 0
	v_mul_f32_e32 v24, v24, v30
	v_mul_f32_e32 v20, v24, v20
	v_mul_f32_e32 v24, 0xbfb8aa3b, v25
	v_exp_f32_e32 v24, v24
	s_nop 0
	v_add_f32_e32 v24, 1.0, v24
	v_rcp_f32_e32 v24, v24
	s_nop 0
	v_mul_f32_e32 v24, v25, v24
	v_mul_f32_e32 v21, v24, v21
	v_cvt_pk_bf16_f32 v30, v20, v21
	v_mul_f32_e32 v20, 0xbfb8aa3b, v26
	v_exp_f32_e32 v20, v20
	v_mul_f32_e32 v21, 0xbfb8aa3b, v27
	v_exp_f32_e32 v21, v21
	v_add_f32_e32 v20, 1.0, v20
	v_rcp_f32_e32 v20, v20
	v_add_f32_e32 v21, 1.0, v21
	v_rcp_f32_e32 v21, v21
	v_mul_f32_e32 v20, v26, v20
	v_mul_f32_e32 v20, v20, v22
	v_mul_f32_e32 v22, 0xbfb8aa3b, v16
	v_exp_f32_e32 v22, v22
	v_mul_f32_e32 v21, v27, v21
	v_mul_f32_e32 v21, v21, v23
	v_cvt_pk_bf16_f32 v31, v20, v21
	v_add_f32_e32 v22, 1.0, v22
	v_rcp_f32_e32 v22, v22
	s_mov_b64 s[98:99], 0xf2000
	v_mul_f32_e32 v16, v16, v22
	v_mul_f32_e32 v12, v16, v12
	v_mul_f32_e32 v16, 0xbfb8aa3b, v17
	v_exp_f32_e32 v16, v16
	v_lshl_add_u64 v[20:21], v[132:133], 0, s[98:99]
	s_mov_b32 s16, s8
	global_store_dwordx4 v[36:37], v[28:31], off
	v_add_f32_e32 v16, 1.0, v16
	v_rcp_f32_e32 v16, v16
	s_nop 0
	v_mul_f32_e32 v16, v17, v16
	v_mul_f32_e32 v13, v16, v13
	v_cvt_pk_bf16_f32 v12, v12, v13
	v_mul_f32_e32 v13, 0xbfb8aa3b, v18
	v_exp_f32_e32 v13, v13
	s_nop 0
	v_add_f32_e32 v13, 1.0, v13
	v_rcp_f32_e32 v13, v13
	s_nop 0
	v_mul_f32_e32 v13, v18, v13
	v_mul_f32_e32 v13, v13, v14
	v_mul_f32_e32 v14, 0xbfb8aa3b, v19
	v_exp_f32_e32 v14, v14
	s_nop 0
	v_add_f32_e32 v14, 1.0, v14
	v_rcp_f32_e32 v14, v14
	s_nop 0
	v_mul_f32_e32 v14, v19, v14
	v_mul_f32_e32 v14, v14, v15
	v_cvt_pk_bf16_f32 v13, v13, v14
	v_mul_f32_e32 v14, 0xbfb8aa3b, v8
	v_exp_f32_e32 v14, v14
	s_nop 0
	v_add_f32_e32 v14, 1.0, v14
	v_rcp_f32_e32 v14, v14
	s_nop 0
	v_mul_f32_e32 v8, v8, v14
	v_mul_f32_e32 v4, v8, v4
	v_mul_f32_e32 v8, 0xbfb8aa3b, v9
	v_exp_f32_e32 v8, v8
	s_nop 0
	v_add_f32_e32 v8, 1.0, v8
	v_rcp_f32_e32 v8, v8
	s_nop 0
	v_mul_f32_e32 v8, v9, v8
	v_mul_f32_e32 v5, v8, v5
	v_cvt_pk_bf16_f32 v14, v4, v5
	v_mul_f32_e32 v4, 0xbfb8aa3b, v10
	v_mul_f32_e32 v5, 0xbfb8aa3b, v11
	v_exp_f32_e32 v4, v4
	v_exp_f32_e32 v5, v5
	v_add_f32_e32 v4, 1.0, v4
	v_add_f32_e32 v5, 1.0, v5
	v_rcp_f32_e32 v4, v4
	v_rcp_f32_e32 v5, v5
	v_mul_f32_e32 v4, v10, v4
	v_mul_f32_e32 v5, v11, v5
	v_mul_f32_e32 v4, v4, v6
	v_mul_f32_e32 v5, v5, v7
	v_cvt_pk_bf16_f32 v15, v4, v5
	global_store_dwordx4 v[20:21], v[12:15], off
	s_cbranch_vccz .LBB0_79
	s_waitcnt vmcnt(0)
	s_cmpk_gt_u32 s95, 0xff
	s_mov_b32 s73, s83
	v_readlane_b32 s79, v255, 21
	s_cbranch_scc1 .LBB0_86
	s_barrier

; #define PG8_STAGE(bufoff, gbase, voff) do { _Pragma("unroll") for (int _i = 0; _i < 2; ++_i) \
;         __builtin_amdgcn_global_load_lds((const unsigned*)((const char*)(gbase) + (voff)[_i]), (LAS unsigned*)(lds + (bufoff) + ldsw + _i * 8192), 16, 0, 0); } while (0)
; #define PG8_LDA(dst, b, h) do { _Pragma("unroll") for (int m = 0; m < 4; ++m) _Pragma("unroll") for (int k = 0; k < 2; ++k) dst[m][k] = *(const LAS bf16x8*)(lds + PG8_SA(b, h) + aoff + m * 2048 + k * 1024); } while (0)
; #define PG8_LDB(dst, b, h) do { _Pragma("unroll") for (int n = 0; n < 2; ++n) _Pragma("unroll") for (int k = 0; k < 2; ++k) dst[n][k] = *(const LAS bf16x8*)(lds + PG8_SB(b, h) + boff + n * 2048 + k * 1024); } while (0)
; #define PG8_MMA(ai, bj, At, Bt) do { __builtin_amdgcn_s_setprio(1); _Pragma("unroll") for (int m = 0; m < 4; ++m) _Pragma("unroll") for (int n = 0; n < 2; ++n) _Pragma("unroll") for (int k = 0; k < 2; ++k) \
;         acc[ai][bj][m][n] = __builtin_amdgcn_mfma_f32_16x16x32_bf16(Bt[n][k], At[m][k], acc[ai][bj][m][n], 0, 0, 0); __builtin_amdgcn_s_setprio(0); } while (0)
; #define PG8_WAIT_V(n) asm volatile("s_waitcnt vmcnt(" #n ")" ::: "memory")
; #define PG8_WAIT_L(n) asm volatile("s_waitcnt lgkmcnt(" #n ")" ::: "memory")
; #define PG8_BAR __builtin_amdgcn_s_barrier()
; #define PG8_SCHED __builtin_amdgcn_sched_barrier(0)
; template <class Epi>
; __device__ __forceinline__ void gemm_phase(LAS unsigned char* lds, const Gemm g, const int G, const int cidx, const Epi& E) {
;     ...
;         for (int t = 0; t < nt; t += 2) {
;             const bool last = (t == nt - 2);
;             const char* a1 = cA + (size_t)(t + 1) * kstep;
;             const char* a2 = last ? nA : cA + (size_t)(t + 2) * kstep; const char* b2 = last ? nB : cB + (size_t)(t + 2) * kstep;
;             const char* a3 = a2 + kstep; const char* b3 = b2 + kstep;
;             PG8_LDB(B0, 0, 0); PG8_LDB(B1, 0, 1); PG8_SCHED; PG8_LDA(At, 0, 0); PG8_STAGE(PG8_SA(1, 1), a1 + hstep, voffA);
;             PG8_WAIT_V(8); PG8_WAIT_L(0); PG8_BAR; PG8_MMA(0, 0, At, B0); PG8_MMA(0, 1, At, B1); PG8_BAR; PG8_SCHED;
;             PG8_LDA(At, 0, 1); PG8_STAGE(PG8_SB(0, 0), b2, voffB); PG8_STAGE(PG8_SB(0, 1), b2 + hstep, voffB); PG8_STAGE(PG8_SA(0, 0), a2, voffA);
;             PG8_WAIT_V(8); PG8_WAIT_L(0); PG8_BAR; PG8_MMA(1, 0, At, B0); PG8_MMA(1, 1, At, B1); PG8_BAR; PG8_SCHED;
.LBB0_216:
	s_add_i32 s87, 0, 0x10000
	v_add_u32_e32 v3, s87, v158
	ds_read_b128 v[132:135], v3
	ds_read_b128 v[140:143], v3 offset:1024
	ds_read_b128 v[160:163], v3 offset:2048
	ds_read_b128 v[164:167], v3 offset:3072
	s_add_i32 s83, 0, 0x14000
	v_add_u32_e32 v3, s83, v158
	ds_read_b128 v[168:171], v3
	ds_read_b128 v[172:175], v3 offset:1024
	ds_read_b128 v[176:179], v3 offset:2048
	ds_read_b128 v[180:183], v3 offset:3072
	v_lshl_add_u64 v[200:201], v[154:155], 0, s[70:71]
	s_add_i32 m0, s19, 0xc000
	ds_read_b128 v[184:187], v159
	ds_read_b128 v[188:191], v159 offset:1024
	ds_read_b128 v[192:195], v159 offset:2048
	ds_read_b128 v[196:199], v159 offset:3072
	ds_read_b128 v[214:217], v159 offset:4096
	ds_read_b128 v[218:221], v159 offset:5120
	ds_read_b128 v[222:225], v159 offset:6144
	ds_read_b128 v[226:229], v159 offset:7168
	s_add_u32 s72, s8, s70
	s_addc_u32 s73, s9, s71
	s_add_u32 s72, s72, 0x100
	s_addc_u32 s73, s73, 0
	s_add_u32 s83, s43, s70
	s_addc_u32 s86, s44, s71
	s_cmpk_eq_i32 s70, 0x700
	s_cselect_b32 s75, s31, s73
	s_cselect_b32 s74, s45, s72
	s_cselect_b32 s73, s29, s86
	s_cselect_b32 s72, s68, s83
	s_add_i32 s83, 0, 0x14000
	global_load_lds_dwordx4 v[200:201], off
	v_lshl_add_u64 v[200:201], v[0:1], 0, s[70:71]
	s_add_i32 m0, s19, 0xe000
	s_nop 0
	global_load_lds_dwordx4 v[200:201], off
	s_waitcnt vmcnt(8)
	s_waitcnt lgkmcnt(0)
	s_barrier
	s_waitcnt lgkmcnt(0)
	v_mfma_f32_16x16x32_bf16 v[64:67], v[132:135], v[184:187], v[64:67]
	v_mfma_f32_16x16x32_bf16 v[72:75], v[160:163], v[184:187], v[72:75]
	v_mfma_f32_16x16x32_bf16 v[92:95], v[132:135], v[192:195], v[92:95]
	v_mfma_f32_16x16x32_bf16 v[96:99], v[160:163], v[192:195], v[96:99]
	v_mfma_f32_16x16x32_bf16 v[116:119], v[132:135], v[214:217], v[116:119]
	v_mfma_f32_16x16x32_bf16 v[124:127], v[160:163], v[214:217], v[124:127]
	v_mfma_f32_16x16x32_bf16 v[112:115], v[132:135], v[222:225], v[112:115]
	v_mfma_f32_16x16x32_bf16 v[100:103], v[160:163], v[222:225], v[100:103]
	v_mfma_f32_16x16x32_bf16 v[64:67], v[140:143], v[188:191], v[64:67]
	v_mfma_f32_16x16x32_bf16 v[72:75], v[164:167], v[188:191], v[72:75]
	v_mfma_f32_16x16x32_bf16 v[92:95], v[140:143], v[196:199], v[92:95]
	v_mfma_f32_16x16x32_bf16 v[96:99], v[164:167], v[196:199], v[96:99]
	v_mfma_f32_16x16x32_bf16 v[116:119], v[140:143], v[218:221], v[116:119]
	v_mfma_f32_16x16x32_bf16 v[124:127], v[164:167], v[218:221], v[124:127]
	v_mfma_f32_16x16x32_bf16 v[112:115], v[140:143], v[226:229], v[112:115]
	v_mfma_f32_16x16x32_bf16 v[100:103], v[164:167], v[226:229], v[100:103]
	v_mfma_f32_16x16x32_bf16 v[76:79], v[168:171], v[184:187], v[76:79]
	v_mfma_f32_16x16x32_bf16 v[84:87], v[176:179], v[184:187], v[84:87]
	v_mfma_f32_16x16x32_bf16 v[104:107], v[168:171], v[192:195], v[104:107]
	v_mfma_f32_16x16x32_bf16 v[108:111], v[176:179], v[192:195], v[108:111]
	v_mfma_f32_16x16x32_bf16 v[128:131], v[168:171], v[214:217], v[128:131]
	v_mfma_f32_16x16x32_bf16 v[120:123], v[176:179], v[214:217], v[120:123]
	v_mfma_f32_16x16x32_bf16 v[88:91], v[168:171], v[222:225], v[88:91]
	v_mfma_f32_16x16x32_bf16 v[80:83], v[176:179], v[222:225], v[80:83]
	v_mfma_f32_16x16x32_bf16 v[76:79], v[172:175], v[188:191], v[76:79]
	v_mfma_f32_16x16x32_bf16 v[84:87], v[180:183], v[188:191], v[84:87]
	v_mfma_f32_16x16x32_bf16 v[104:107], v[172:175], v[196:199], v[104:107]
	v_mfma_f32_16x16x32_bf16 v[108:111], v[180:183], v[196:199], v[108:111]
	v_mfma_f32_16x16x32_bf16 v[128:131], v[172:175], v[218:221], v[128:131]
	v_mfma_f32_16x16x32_bf16 v[120:123], v[180:183], v[218:221], v[120:123]
	v_mfma_f32_16x16x32_bf16 v[88:91], v[172:175], v[226:229], v[88:91]
	v_mfma_f32_16x16x32_bf16 v[80:83], v[180:183], v[226:229], v[80:83]
	s_barrier
	s_add_i32 s86, s87, s40
	v_lshl_add_u64 v[200:201], s[72:73], 0, v[146:147]
	s_mov_b32 m0, s86
	ds_read_b128 v[184:187], v159 offset:16384
	ds_read_b128 v[188:191], v159 offset:17408
	ds_read_b128 v[192:195], v159 offset:18432
	ds_read_b128 v[196:199], v159 offset:19456
	ds_read_b128 v[214:217], v159 offset:20480
	ds_read_b128 v[218:221], v159 offset:21504
	ds_read_b128 v[222:225], v159 offset:22528
	ds_read_b128 v[226:229], v159 offset:23552
	global_load_lds_dwordx4 v[200:201], off
	s_add_i32 m0, s86, 0x2000
	s_add_u32 s86, s72, 0x40000
	v_lshl_add_u64 v[230:231], s[72:73], 0, v[148:149]
	s_addc_u32 s87, s73, 0
	s_add_i32 s83, s83, s40
	global_load_lds_dwordx4 v[230:231], off
	v_lshl_add_u64 v[232:233], s[86:87], 0, v[146:147]
	s_mov_b32 m0, s83
	v_lshl_add_u64 v[234:235], s[74:75], 0, v[148:149]
	global_load_lds_dwordx4 v[232:233], off
	v_lshl_add_u64 v[232:233], s[86:87], 0, v[148:149]
	s_add_i32 m0, s83, 0x2000
	s_nop 0
	global_load_lds_dwordx4 v[232:233], off
	v_lshl_add_u64 v[232:233], s[74:75], 0, v[146:147]
	s_mov_b32 m0, s19
	s_nop 0
	global_load_lds_dwordx4 v[232:233], off
	s_mov_b32 m0, s76
	s_nop 0
	global_load_lds_dwordx4 v[234:235], off
	s_waitcnt vmcnt(8)
	s_waitcnt lgkmcnt(0)
	s_barrier
; #define PG8_STAGE(bufoff, gbase, voff) do { _Pragma("unroll") for (int _i = 0; _i < 2; ++_i) \
;         __builtin_amdgcn_global_load_lds((const unsigned*)((const char*)(gbase) + (voff)[_i]), (LAS unsigned*)(lds + (bufoff) + ldsw + _i * 8192), 16, 0, 0); } while (0)
; #define PG8_LDA(dst, b, h) do { _Pragma("unroll") for (int m = 0; m < 4; ++m) _Pragma("unroll") for (int k = 0; k < 2; ++k) dst[m][k] = *(const LAS bf16x8*)(lds + PG8_SA(b, h) + aoff + m * 2048 + k * 1024); } while (0)
; #define PG8_LDB(dst, b, h) do { _Pragma("unroll") for (int n = 0; n < 2; ++n) _Pragma("unroll") for (int k = 0; k < 2; ++k) dst[n][k] = *(const LAS bf16x8*)(lds + PG8_SB(b, h) + boff + n * 2048 + k * 1024); } while (0)
; #define PG8_MMA(ai, bj, At, Bt) do { __builtin_amdgcn_s_setprio(1); _Pragma("unroll") for (int m = 0; m < 4; ++m) _Pragma("unroll") for (int n = 0; n < 2; ++n) _Pragma("unroll") for (int k = 0; k < 2; ++k) \
;         acc[ai][bj][m][n] = __builtin_amdgcn_mfma_f32_16x16x32_bf16(Bt[n][k], At[m][k], acc[ai][bj][m][n], 0, 0, 0); __builtin_amdgcn_s_setprio(0); } while (0)
; #define PG8_WAIT_V(n) asm volatile("s_waitcnt vmcnt(" #n ")" ::: "memory")
; #define PG8_WAIT_L(n) asm volatile("s_waitcnt lgkmcnt(" #n ")" ::: "memory")
; #define PG8_BAR __builtin_amdgcn_s_barrier()
; #define PG8_SCHED __builtin_amdgcn_sched_barrier(0)
; template <class Epi>
; __device__ __forceinline__ void gemm_phase(LAS unsigned char* lds, const Gemm g, const int G, const int cidx, const Epi& E) {
;     ...
;             PG8_WAIT_V(8); PG8_WAIT_L(0); PG8_BAR; PG8_MMA(1, 0, At, B0); PG8_MMA(1, 1, At, B1); PG8_BAR; PG8_SCHED;
;             PG8_LDB(B0, 1, 0); PG8_LDB(B1, 1, 1); PG8_SCHED; PG8_LDA(At, 1, 0); PG8_STAGE(PG8_SA(0, 1), a2 + hstep, voffA);
;             PG8_WAIT_V(8); PG8_WAIT_L(0); PG8_BAR; PG8_MMA(0, 0, At, B0); PG8_MMA(0, 1, At, B1); PG8_BAR; PG8_SCHED;
	s_waitcnt lgkmcnt(0)
	v_mfma_f32_16x16x32_bf16 v[68:71], v[132:135], v[184:187], v[68:71]
	v_mfma_f32_16x16x32_bf16 v[60:63], v[160:163], v[184:187], v[60:63]
	v_mfma_f32_16x16x32_bf16 v[48:51], v[132:135], v[192:195], v[48:51]
	v_mfma_f32_16x16x32_bf16 v[44:47], v[160:163], v[192:195], v[44:47]
	v_mfma_f32_16x16x32_bf16 v[32:35], v[132:135], v[214:217], v[32:35]
	v_mfma_f32_16x16x32_bf16 v[28:31], v[160:163], v[214:217], v[28:31]
	v_mfma_f32_16x16x32_bf16 v[16:19], v[132:135], v[222:225], v[16:19]
	v_mfma_f32_16x16x32_bf16 v[12:15], v[160:163], v[222:225], v[12:15]
	v_mfma_f32_16x16x32_bf16 v[68:71], v[140:143], v[188:191], v[68:71]
	v_mfma_f32_16x16x32_bf16 v[60:63], v[164:167], v[188:191], v[60:63]
	v_mfma_f32_16x16x32_bf16 v[48:51], v[140:143], v[196:199], v[48:51]
	v_mfma_f32_16x16x32_bf16 v[44:47], v[164:167], v[196:199], v[44:47]
	v_mfma_f32_16x16x32_bf16 v[32:35], v[140:143], v[218:221], v[32:35]
	v_mfma_f32_16x16x32_bf16 v[28:31], v[164:167], v[218:221], v[28:31]
	v_mfma_f32_16x16x32_bf16 v[16:19], v[140:143], v[226:229], v[16:19]
	v_mfma_f32_16x16x32_bf16 v[12:15], v[164:167], v[226:229], v[12:15]
	v_mfma_f32_16x16x32_bf16 v[56:59], v[168:171], v[184:187], v[56:59]
	v_mfma_f32_16x16x32_bf16 v[52:55], v[176:179], v[184:187], v[52:55]
	v_mfma_f32_16x16x32_bf16 v[40:43], v[168:171], v[192:195], v[40:43]
	v_mfma_f32_16x16x32_bf16 v[36:39], v[176:179], v[192:195], v[36:39]
	v_mfma_f32_16x16x32_bf16 v[24:27], v[168:171], v[214:217], v[24:27]
	v_mfma_f32_16x16x32_bf16 v[20:23], v[176:179], v[214:217], v[20:23]
	v_mfma_f32_16x16x32_bf16 v[8:11], v[168:171], v[222:225], v[8:11]
	v_mfma_f32_16x16x32_bf16 v[4:7], v[176:179], v[222:225], v[4:7]
	v_mfma_f32_16x16x32_bf16 v[56:59], v[172:175], v[188:191], v[56:59]
	v_mfma_f32_16x16x32_bf16 v[52:55], v[180:183], v[188:191], v[52:55]
	v_mfma_f32_16x16x32_bf16 v[40:43], v[172:175], v[196:199], v[40:43]
	v_mfma_f32_16x16x32_bf16 v[36:39], v[180:183], v[196:199], v[36:39]
	v_mfma_f32_16x16x32_bf16 v[24:27], v[172:175], v[218:221], v[24:27]
	v_mfma_f32_16x16x32_bf16 v[20:23], v[180:183], v[218:221], v[20:23]
	v_mfma_f32_16x16x32_bf16 v[8:11], v[172:175], v[226:229], v[8:11]
	v_mfma_f32_16x16x32_bf16 v[4:7], v[180:183], v[226:229], v[4:7]
	s_barrier
	s_add_i32 s83, 0, 0x18000
	v_add_u32_e32 v3, s83, v158
	s_add_i32 s86, 0, 0x1c000
	ds_read_b128 v[132:135], v3
	ds_read_b128 v[140:143], v3 offset:1024
	ds_read_b128 v[160:163], v3 offset:2048
	ds_read_b128 v[164:167], v3 offset:3072
	v_add_u32_e32 v3, s86, v158
	ds_read_b128 v[168:171], v3
	ds_read_b128 v[172:175], v3 offset:1024
	ds_read_b128 v[176:179], v3 offset:2048
	ds_read_b128 v[180:183], v3 offset:3072
	s_add_u32 s74, s74, 0x40000
	s_addc_u32 s75, s75, 0
	s_mov_b32 m0, s84
	v_lshl_add_u64 v[236:237], s[74:75], 0, v[146:147]
	ds_read_b128 v[184:187], v159 offset:32768
	ds_read_b128 v[188:191], v159 offset:33792
	ds_read_b128 v[192:195], v159 offset:34816
	ds_read_b128 v[196:199], v159 offset:35840
	ds_read_b128 v[214:217], v159 offset:36864
	ds_read_b128 v[218:221], v159 offset:37888
	ds_read_b128 v[222:225], v159 offset:38912
	ds_read_b128 v[226:229], v159 offset:39936
	global_load_lds_dwordx4 v[236:237], off
	v_lshl_add_u64 v[236:237], s[74:75], 0, v[148:149]
	s_mov_b32 m0, s97
	s_nop 0
	global_load_lds_dwordx4 v[236:237], off
	s_waitcnt vmcnt(8)
	s_waitcnt lgkmcnt(0)
	s_barrier
	s_waitcnt lgkmcnt(0)
	v_mfma_f32_16x16x32_bf16 v[64:67], v[132:135], v[184:187], v[64:67]
	v_mfma_f32_16x16x32_bf16 v[72:75], v[160:163], v[184:187], v[72:75]
	v_mfma_f32_16x16x32_bf16 v[92:95], v[132:135], v[192:195], v[92:95]
	v_mfma_f32_16x16x32_bf16 v[96:99], v[160:163], v[192:195], v[96:99]
	v_mfma_f32_16x16x32_bf16 v[116:119], v[132:135], v[214:217], v[116:119]
	v_mfma_f32_16x16x32_bf16 v[124:127], v[160:163], v[214:217], v[124:127]
	v_mfma_f32_16x16x32_bf16 v[112:115], v[132:135], v[222:225], v[112:115]
	v_mfma_f32_16x16x32_bf16 v[100:103], v[160:163], v[222:225], v[100:103]
	v_mfma_f32_16x16x32_bf16 v[64:67], v[140:143], v[188:191], v[64:67]
	v_mfma_f32_16x16x32_bf16 v[72:75], v[164:167], v[188:191], v[72:75]
	v_mfma_f32_16x16x32_bf16 v[92:95], v[140:143], v[196:199], v[92:95]
	v_mfma_f32_16x16x32_bf16 v[96:99], v[164:167], v[196:199], v[96:99]
	v_mfma_f32_16x16x32_bf16 v[116:119], v[140:143], v[218:221], v[116:119]
	v_mfma_f32_16x16x32_bf16 v[124:127], v[164:167], v[218:221], v[124:127]
	v_mfma_f32_16x16x32_bf16 v[112:115], v[140:143], v[226:229], v[112:115]
	v_mfma_f32_16x16x32_bf16 v[100:103], v[164:167], v[226:229], v[100:103]
	v_mfma_f32_16x16x32_bf16 v[76:79], v[168:171], v[184:187], v[76:79]
	v_mfma_f32_16x16x32_bf16 v[84:87], v[176:179], v[184:187], v[84:87]
	v_mfma_f32_16x16x32_bf16 v[104:107], v[168:171], v[192:195], v[104:107]
	v_mfma_f32_16x16x32_bf16 v[108:111], v[176:179], v[192:195], v[108:111]
	v_mfma_f32_16x16x32_bf16 v[128:131], v[168:171], v[214:217], v[128:131]
	v_mfma_f32_16x16x32_bf16 v[120:123], v[176:179], v[214:217], v[120:123]
	v_mfma_f32_16x16x32_bf16 v[88:91], v[168:171], v[222:225], v[88:91]
	v_mfma_f32_16x16x32_bf16 v[80:83], v[176:179], v[222:225], v[80:83]
	v_mfma_f32_16x16x32_bf16 v[76:79], v[172:175], v[188:191], v[76:79]
	v_mfma_f32_16x16x32_bf16 v[84:87], v[180:183], v[188:191], v[84:87]
	v_mfma_f32_16x16x32_bf16 v[104:107], v[172:175], v[196:199], v[104:107]
	v_mfma_f32_16x16x32_bf16 v[108:111], v[180:183], v[196:199], v[108:111]
	v_mfma_f32_16x16x32_bf16 v[128:131], v[172:175], v[218:221], v[128:131]
	v_mfma_f32_16x16x32_bf16 v[120:123], v[180:183], v[218:221], v[120:123]
	v_mfma_f32_16x16x32_bf16 v[88:91], v[172:175], v[226:229], v[88:91]
	v_mfma_f32_16x16x32_bf16 v[80:83], v[180:183], v[226:229], v[80:83]
	s_barrier
; #define PG8_STAGE(bufoff, gbase, voff) do { _Pragma("unroll") for (int _i = 0; _i < 2; ++_i) \
;         __builtin_amdgcn_global_load_lds((const unsigned*)((const char*)(gbase) + (voff)[_i]), (LAS unsigned*)(lds + (bufoff) + ldsw + _i * 8192), 16, 0, 0); } while (0)
; #define PG8_LDA(dst, b, h) do { _Pragma("unroll") for (int m = 0; m < 4; ++m) _Pragma("unroll") for (int k = 0; k < 2; ++k) dst[m][k] = *(const LAS bf16x8*)(lds + PG8_SA(b, h) + aoff + m * 2048 + k * 1024); } while (0)
; #define PG8_MMA(ai, bj, At, Bt) do { __builtin_amdgcn_s_setprio(1); _Pragma("unroll") for (int m = 0; m < 4; ++m) _Pragma("unroll") for (int n = 0; n < 2; ++n) _Pragma("unroll") for (int k = 0; k < 2; ++k) \
;         acc[ai][bj][m][n] = __builtin_amdgcn_mfma_f32_16x16x32_bf16(Bt[n][k], At[m][k], acc[ai][bj][m][n], 0, 0, 0); __builtin_amdgcn_s_setprio(0); } while (0)
; #define PG8_WAIT_V(n) asm volatile("s_waitcnt vmcnt(" #n ")" ::: "memory")
; #define PG8_WAIT_L(n) asm volatile("s_waitcnt lgkmcnt(" #n ")" ::: "memory")
; #define PG8_BAR __builtin_amdgcn_s_barrier()
; #define PG8_SCHED __builtin_amdgcn_sched_barrier(0)
; template <class Epi>
; __device__ __forceinline__ void gemm_phase(LAS unsigned char* lds, const Gemm g, const int G, const int cidx, const Epi& E) {
;     ...
;             PG8_LDA(At, 1, 1); PG8_STAGE(PG8_SB(1, 0), b3, voffB); PG8_STAGE(PG8_SB(1, 1), b3 + hstep, voffB); PG8_STAGE(PG8_SA(1, 0), a3, voffA);
;             PG8_WAIT_V(8); PG8_WAIT_L(0); PG8_BAR; PG8_MMA(1, 0, At, B0); PG8_MMA(1, 1, At, B1); PG8_BAR; PG8_SCHED;
;         }
;         if constexpr (!Epi::AFTER_DRAIN) E(acc, cur, wr, wc, fr, fq);
;         if (!has_next) break;
; #pragma unroll
;         for (int a = 0; a < 2; ++a)
; #pragma unroll
;             for (int b = 0; b < 2; ++b)
; #pragma unroll
;                 for (int m = 0; m < 4; ++m)
; #pragma unroll
;                     for (int n = 0; n < 2; ++n) acc[a][b][m][n] = ZERO4;
;         cur = nxt; cA = nA; cB = nB; ++ui;
	s_add_i32 s74, s83, s40
	v_lshl_add_u64 v[200:201], v[200:201], 0, s[46:47]
	s_mov_b32 m0, s74
	ds_read_b128 v[184:187], v159 offset:49152
	ds_read_b128 v[188:191], v159 offset:50176
	ds_read_b128 v[192:195], v159 offset:51200
	ds_read_b128 v[196:199], v159 offset:52224
	ds_read_b128 v[214:217], v159 offset:53248
	ds_read_b128 v[218:221], v159 offset:54272
	ds_read_b128 v[222:225], v159 offset:55296
	ds_read_b128 v[226:229], v159 offset:56320
	global_load_lds_dwordx4 v[200:201], off
	s_add_i32 m0, s74, 0x2000
	s_add_u32 s72, s72, 0x40080
	v_lshl_add_u64 v[200:201], v[230:231], 0, s[46:47]
	s_addc_u32 s73, s73, 0
	s_add_i32 s74, s86, s40
	global_load_lds_dwordx4 v[200:201], off
	v_lshl_add_u64 v[200:201], s[72:73], 0, v[146:147]
	s_mov_b32 m0, s74
	s_nop 0
	global_load_lds_dwordx4 v[200:201], off
	v_lshl_add_u64 v[200:201], s[72:73], 0, v[148:149]
	s_add_i32 m0, s74, 0x2000
	s_nop 0
	global_load_lds_dwordx4 v[200:201], off
	v_lshl_add_u64 v[200:201], v[232:233], 0, s[46:47]
	s_mov_b32 m0, s0
	s_nop 0
	global_load_lds_dwordx4 v[200:201], off
	v_lshl_add_u64 v[200:201], v[234:235], 0, s[46:47]
	s_mov_b32 m0, s2
	s_nop 0
	global_load_lds_dwordx4 v[200:201], off
	s_waitcnt vmcnt(8)
	s_waitcnt lgkmcnt(0)
	s_barrier
	s_waitcnt lgkmcnt(0)
	v_mfma_f32_16x16x32_bf16 v[68:71], v[132:135], v[184:187], v[68:71]
	v_mfma_f32_16x16x32_bf16 v[60:63], v[160:163], v[184:187], v[60:63]
	v_mfma_f32_16x16x32_bf16 v[48:51], v[132:135], v[192:195], v[48:51]
	v_mfma_f32_16x16x32_bf16 v[44:47], v[160:163], v[192:195], v[44:47]
	v_mfma_f32_16x16x32_bf16 v[32:35], v[132:135], v[214:217], v[32:35]
	v_mfma_f32_16x16x32_bf16 v[28:31], v[160:163], v[214:217], v[28:31]
	v_mfma_f32_16x16x32_bf16 v[16:19], v[132:135], v[222:225], v[16:19]
	v_mfma_f32_16x16x32_bf16 v[12:15], v[160:163], v[222:225], v[12:15]
	v_mfma_f32_16x16x32_bf16 v[68:71], v[140:143], v[188:191], v[68:71]
	v_mfma_f32_16x16x32_bf16 v[60:63], v[164:167], v[188:191], v[60:63]
	v_mfma_f32_16x16x32_bf16 v[48:51], v[140:143], v[196:199], v[48:51]
	v_mfma_f32_16x16x32_bf16 v[44:47], v[164:167], v[196:199], v[44:47]
	v_mfma_f32_16x16x32_bf16 v[32:35], v[140:143], v[218:221], v[32:35]
	v_mfma_f32_16x16x32_bf16 v[28:31], v[164:167], v[218:221], v[28:31]
	v_mfma_f32_16x16x32_bf16 v[16:19], v[140:143], v[226:229], v[16:19]
	v_mfma_f32_16x16x32_bf16 v[12:15], v[164:167], v[226:229], v[12:15]
	v_mfma_f32_16x16x32_bf16 v[56:59], v[168:171], v[184:187], v[56:59]
	v_mfma_f32_16x16x32_bf16 v[52:55], v[176:179], v[184:187], v[52:55]
	v_mfma_f32_16x16x32_bf16 v[40:43], v[168:171], v[192:195], v[40:43]
	v_mfma_f32_16x16x32_bf16 v[36:39], v[176:179], v[192:195], v[36:39]
	v_mfma_f32_16x16x32_bf16 v[24:27], v[168:171], v[214:217], v[24:27]
	v_mfma_f32_16x16x32_bf16 v[20:23], v[176:179], v[214:217], v[20:23]
	v_mfma_f32_16x16x32_bf16 v[8:11], v[168:171], v[222:225], v[8:11]
	v_mfma_f32_16x16x32_bf16 v[4:7], v[176:179], v[222:225], v[4:7]
	v_mfma_f32_16x16x32_bf16 v[56:59], v[172:175], v[188:191], v[56:59]
	v_mfma_f32_16x16x32_bf16 v[52:55], v[180:183], v[188:191], v[52:55]
	v_mfma_f32_16x16x32_bf16 v[40:43], v[172:175], v[196:199], v[40:43]
	v_mfma_f32_16x16x32_bf16 v[36:39], v[180:183], v[196:199], v[36:39]
	v_mfma_f32_16x16x32_bf16 v[24:27], v[172:175], v[218:221], v[24:27]
	v_mfma_f32_16x16x32_bf16 v[20:23], v[180:183], v[218:221], v[20:23]
	v_mfma_f32_16x16x32_bf16 v[8:11], v[172:175], v[226:229], v[8:11]
	v_mfma_f32_16x16x32_bf16 v[4:7], v[180:183], v[226:229], v[4:7]
	s_add_i32 s77, s77, 2
	s_add_u32 s70, s70, 0x100
	s_addc_u32 s71, s71, 0
	s_cmp_gt_u32 s77, 13
	s_barrier
	s_cbranch_scc0 .LBB0_216
	s_add_u32 s70, s43, 0xffffff00
	s_addc_u32 s71, s44, -1
	s_andn2_b64 vcc, exec, s[6:7]
	s_cbranch_vccnz .LBB0_219
	v_mov_b32_e32 v4, 0
	s_mov_b32 s20, s28
	s_mov_b32 s18, s30
	s_mov_b64 s[8:9], s[36:37]
	s_mov_b32 s38, s33
	v_mov_b32_e32 v5, v4
	v_mov_b32_e32 v6, v4
	v_mov_b32_e32 v7, v4
	v_mov_b32_e32 v8, v4
	v_mov_b32_e32 v9, v4
	v_mov_b32_e32 v10, v4
	v_mov_b32_e32 v11, v4
	v_mov_b32_e32 v20, v4
	v_mov_b32_e32 v21, v4
	v_mov_b32_e32 v22, v4
	v_mov_b32_e32 v23, v4
	v_mov_b32_e32 v24, v4
	v_mov_b32_e32 v25, v4
	v_mov_b32_e32 v26, v4
	v_mov_b32_e32 v27, v4
	v_mov_b32_e32 v36, v4
	v_mov_b32_e32 v37, v4
	v_mov_b32_e32 v38, v4
	v_mov_b32_e32 v39, v4
	v_mov_b32_e32 v40, v4
	v_mov_b32_e32 v41, v4
	v_mov_b32_e32 v42, v4
	v_mov_b32_e32 v43, v4
	v_mov_b32_e32 v52, v4
	v_mov_b32_e32 v53, v4
	v_mov_b32_e32 v54, v4
	v_mov_b32_e32 v55, v4
	v_mov_b32_e32 v56, v4
	v_mov_b32_e32 v57, v4
	v_mov_b32_e32 v58, v4
	v_mov_b32_e32 v59, v4
	v_mov_b32_e32 v12, v4
	v_mov_b32_e32 v13, v4
	v_mov_b32_e32 v14, v4
	v_mov_b32_e32 v15, v4
	v_mov_b32_e32 v16, v4
	v_mov_b32_e32 v17, v4
	v_mov_b32_e32 v18, v4
	v_mov_b32_e32 v19, v4
	v_mov_b32_e32 v28, v4
	v_mov_b32_e32 v29, v4
	v_mov_b32_e32 v30, v4
	v_mov_b32_e32 v31, v4
	v_mov_b32_e32 v32, v4
	v_mov_b32_e32 v33, v4
	v_mov_b32_e32 v34, v4
	v_mov_b32_e32 v35, v4
	v_mov_b32_e32 v44, v4
	v_mov_b32_e32 v45, v4
	v_mov_b32_e32 v46, v4
	v_mov_b32_e32 v47, v4
	v_mov_b32_e32 v48, v4
	v_mov_b32_e32 v49, v4
	v_mov_b32_e32 v50, v4
	v_mov_b32_e32 v51, v4
	v_mov_b32_e32 v60, v4
	v_mov_b32_e32 v61, v4
	v_mov_b32_e32 v62, v4
	v_mov_b32_e32 v63, v4
	v_mov_b32_e32 v68, v4
	v_mov_b32_e32 v69, v4
	v_mov_b32_e32 v70, v4
	v_mov_b32_e32 v71, v4
	v_mov_b32_e32 v80, v4
	v_mov_b32_e32 v81, v4
	v_mov_b32_e32 v82, v4
	v_mov_b32_e32 v83, v4
	v_mov_b32_e32 v88, v4
	v_mov_b32_e32 v89, v4
	v_mov_b32_e32 v90, v4
	v_mov_b32_e32 v91, v4
	v_mov_b32_e32 v120, v4
	v_mov_b32_e32 v121, v4
	v_mov_b32_e32 v122, v4
	v_mov_b32_e32 v123, v4
	v_mov_b32_e32 v128, v4
	v_mov_b32_e32 v129, v4
	v_mov_b32_e32 v130, v4
	v_mov_b32_e32 v131, v4
	v_mov_b32_e32 v108, v4
	v_mov_b32_e32 v109, v4
	v_mov_b32_e32 v110, v4
	v_mov_b32_e32 v111, v4
	v_mov_b32_e32 v104, v4
	v_mov_b32_e32 v105, v4
	v_mov_b32_e32 v106, v4
	v_mov_b32_e32 v107, v4
	v_mov_b32_e32 v84, v4
	v_mov_b32_e32 v85, v4
	v_mov_b32_e32 v86, v4
	v_mov_b32_e32 v87, v4
	v_mov_b32_e32 v76, v4
	v_mov_b32_e32 v77, v4
	v_mov_b32_e32 v78, v4
	v_mov_b32_e32 v79, v4
	v_mov_b32_e32 v100, v4
	v_mov_b32_e32 v101, v4
	v_mov_b32_e32 v102, v4
	v_mov_b32_e32 v103, v4
	v_mov_b32_e32 v112, v4
	v_mov_b32_e32 v113, v4
	v_mov_b32_e32 v114, v4
	v_mov_b32_e32 v115, v4
	v_mov_b32_e32 v124, v4
	v_mov_b32_e32 v125, v4
	v_mov_b32_e32 v126, v4
	v_mov_b32_e32 v127, v4
	v_mov_b32_e32 v116, v4
	v_mov_b32_e32 v117, v4
	v_mov_b32_e32 v118, v4
	v_mov_b32_e32 v119, v4
	v_mov_b32_e32 v96, v4
	v_mov_b32_e32 v97, v4
	v_mov_b32_e32 v98, v4
	v_mov_b32_e32 v99, v4
	v_mov_b32_e32 v92, v4
	v_mov_b32_e32 v93, v4
	v_mov_b32_e32 v94, v4
	v_mov_b32_e32 v95, v4
	v_mov_b32_e32 v72, v4
	v_mov_b32_e32 v73, v4
	v_mov_b32_e32 v74, v4
	v_mov_b32_e32 v75, v4
	v_mov_b32_e32 v64, v4
	v_mov_b32_e32 v65, v4
	v_mov_b32_e32 v66, v4
	v_mov_b32_e32 v67, v4
	s_mov_b32 s83, 0x18000
	s_mov_b32 s86, 0x3fb8aa3b
	s_andn2_b64 vcc, exec, s[4:5]
	s_cbranch_vccnz .LBB0_220
	s_branch .LBB0_221

; #define PG8_STAGE(bufoff, gbase, voff) do { _Pragma("unroll") for (int _i = 0; _i < 2; ++_i) \
;         __builtin_amdgcn_global_load_lds((const unsigned*)((const char*)(gbase) + (voff)[_i]), (LAS unsigned*)(lds + (bufoff) + ldsw + _i * 8192), 16, 0, 0); } while (0)
; #define PG8_LDA(dst, b, h) do { _Pragma("unroll") for (int m = 0; m < 4; ++m) _Pragma("unroll") for (int k = 0; k < 2; ++k) dst[m][k] = *(const LAS bf16x8*)(lds + PG8_SA(b, h) + aoff + m * 2048 + k * 1024); } while (0)
; #define PG8_LDB(dst, b, h) do { _Pragma("unroll") for (int n = 0; n < 2; ++n) _Pragma("unroll") for (int k = 0; k < 2; ++k) dst[n][k] = *(const LAS bf16x8*)(lds + PG8_SB(b, h) + boff + n * 2048 + k * 1024); } while (0)
; #define PG8_MMA(ai, bj, At, Bt) do { __builtin_amdgcn_s_setprio(1); _Pragma("unroll") for (int m = 0; m < 4; ++m) _Pragma("unroll") for (int n = 0; n < 2; ++n) _Pragma("unroll") for (int k = 0; k < 2; ++k) \
;         acc[ai][bj][m][n] = __builtin_amdgcn_mfma_f32_16x16x32_bf16(Bt[n][k], At[m][k], acc[ai][bj][m][n], 0, 0, 0); __builtin_amdgcn_s_setprio(0); } while (0)
; #define PG8_WAIT_V(n) asm volatile("s_waitcnt vmcnt(" #n ")" ::: "memory")
; #define PG8_WAIT_L(n) asm volatile("s_waitcnt lgkmcnt(" #n ")" ::: "memory")
; #define PG8_BAR __builtin_amdgcn_s_barrier()
; #define PG8_SCHED __builtin_amdgcn_sched_barrier(0)
; template <class Epi>
; __device__ __forceinline__ void gemm_phase(LAS unsigned char* lds, const Gemm g, const int G, const int cidx, const Epi& E) {
;     ...
;         for (int t = 0; t < nt; t += 2) {
;             const bool last = (t == nt - 2);
;             const char* a1 = cA + (size_t)(t + 1) * kstep;
;             const char* a2 = last ? nA : cA + (size_t)(t + 2) * kstep; const char* b2 = last ? nB : cB + (size_t)(t + 2) * kstep;
;             const char* a3 = a2 + kstep; const char* b3 = b2 + kstep;
;             PG8_LDB(B0, 0, 0); PG8_LDB(B1, 0, 1); PG8_SCHED; PG8_LDA(At, 0, 0); PG8_STAGE(PG8_SA(1, 1), a1 + hstep, voffA);
;             PG8_WAIT_V(8); PG8_WAIT_L(0); PG8_BAR; PG8_MMA(0, 0, At, B0); PG8_MMA(0, 1, At, B1); PG8_BAR; PG8_SCHED;
;             PG8_LDA(At, 0, 1); PG8_STAGE(PG8_SB(0, 0), b2, voffB); PG8_STAGE(PG8_SB(0, 1), b2 + hstep, voffB); PG8_STAGE(PG8_SA(0, 0), a2, voffA);
;             PG8_WAIT_V(8); PG8_WAIT_L(0); PG8_BAR; PG8_MMA(1, 0, At, B0); PG8_MMA(1, 1, At, B1); PG8_BAR; PG8_SCHED;
.LBB0_450:
	s_add_i32 s83, 0, 0x10000
	v_add_u32_e32 v3, s83, v157
	ds_read_b128 v[132:135], v3
	ds_read_b128 v[140:143], v3 offset:1024
	ds_read_b128 v[160:163], v3 offset:2048
	ds_read_b128 v[164:167], v3 offset:3072
	s_add_i32 s68, 0, 0x14000
	v_add_u32_e32 v3, s68, v157
	ds_read_b128 v[168:171], v3
	ds_read_b128 v[172:175], v3 offset:1024
	ds_read_b128 v[176:179], v3 offset:2048
	ds_read_b128 v[180:183], v3 offset:3072
	v_lshl_add_u64 v[200:201], v[154:155], 0, s[24:25]
	s_add_i32 m0, s71, 0xc000
	ds_read_b128 v[184:187], v159
	ds_read_b128 v[188:191], v159 offset:1024
	ds_read_b128 v[192:195], v159 offset:2048
	ds_read_b128 v[196:199], v159 offset:3072
	ds_read_b128 v[214:217], v159 offset:4096
	ds_read_b128 v[218:221], v159 offset:5120
	ds_read_b128 v[222:225], v159 offset:6144
	ds_read_b128 v[226:229], v159 offset:7168
	s_add_u32 s26, s10, s24
	s_addc_u32 s27, s11, s25
	s_add_u32 s26, s26, 0x100
	s_addc_u32 s27, s27, 0
	s_add_u32 s68, s43, s24
	s_addc_u32 s77, s44, s25
	s_cmpk_eq_i32 s24, 0x1500
	s_cselect_b32 s29, s21, s27
	s_cselect_b32 s28, s20, s26
	s_cselect_b32 s27, s9, s77
	s_cselect_b32 s26, s8, s68
	s_add_i32 s68, 0, 0x14000
	global_load_lds_dwordx4 v[200:201], off
	v_lshl_add_u64 v[200:201], v[0:1], 0, s[24:25]
	s_add_i32 m0, s71, 0xe000
	s_nop 0
	global_load_lds_dwordx4 v[200:201], off
	s_waitcnt vmcnt(8)
	s_waitcnt lgkmcnt(0)
	s_barrier
	s_waitcnt lgkmcnt(0)
	v_mfma_f32_16x16x32_bf16 v[100:103], v[132:135], v[184:187], v[100:103]
	v_mfma_f32_16x16x32_bf16 v[108:111], v[160:163], v[184:187], v[108:111]
	v_mfma_f32_16x16x32_bf16 v[120:123], v[132:135], v[192:195], v[120:123]
	v_mfma_f32_16x16x32_bf16 v[128:131], v[160:163], v[192:195], v[128:131]
	v_mfma_f32_16x16x32_bf16 v[96:99], v[132:135], v[214:217], v[96:99]
	v_mfma_f32_16x16x32_bf16 v[92:95], v[160:163], v[214:217], v[92:95]
	v_mfma_f32_16x16x32_bf16 v[80:83], v[132:135], v[222:225], v[80:83]
	v_mfma_f32_16x16x32_bf16 v[76:79], v[160:163], v[222:225], v[76:79]
	v_mfma_f32_16x16x32_bf16 v[100:103], v[140:143], v[188:191], v[100:103]
	v_mfma_f32_16x16x32_bf16 v[108:111], v[164:167], v[188:191], v[108:111]
	v_mfma_f32_16x16x32_bf16 v[120:123], v[140:143], v[196:199], v[120:123]
	v_mfma_f32_16x16x32_bf16 v[128:131], v[164:167], v[196:199], v[128:131]
	v_mfma_f32_16x16x32_bf16 v[96:99], v[140:143], v[218:221], v[96:99]
	v_mfma_f32_16x16x32_bf16 v[92:95], v[164:167], v[218:221], v[92:95]
	v_mfma_f32_16x16x32_bf16 v[80:83], v[140:143], v[226:229], v[80:83]
	v_mfma_f32_16x16x32_bf16 v[76:79], v[164:167], v[226:229], v[76:79]
	v_mfma_f32_16x16x32_bf16 v[116:119], v[168:171], v[184:187], v[116:119]
	v_mfma_f32_16x16x32_bf16 v[124:127], v[176:179], v[184:187], v[124:127]
	v_mfma_f32_16x16x32_bf16 v[112:115], v[168:171], v[192:195], v[112:115]
	v_mfma_f32_16x16x32_bf16 v[104:107], v[176:179], v[192:195], v[104:107]
	v_mfma_f32_16x16x32_bf16 v[88:91], v[168:171], v[214:217], v[88:91]
	v_mfma_f32_16x16x32_bf16 v[84:87], v[176:179], v[214:217], v[84:87]
	v_mfma_f32_16x16x32_bf16 v[72:75], v[168:171], v[222:225], v[72:75]
	v_mfma_f32_16x16x32_bf16 v[68:71], v[176:179], v[222:225], v[68:71]
	v_mfma_f32_16x16x32_bf16 v[116:119], v[172:175], v[188:191], v[116:119]
	v_mfma_f32_16x16x32_bf16 v[124:127], v[180:183], v[188:191], v[124:127]
	v_mfma_f32_16x16x32_bf16 v[112:115], v[172:175], v[196:199], v[112:115]
	v_mfma_f32_16x16x32_bf16 v[104:107], v[180:183], v[196:199], v[104:107]
	v_mfma_f32_16x16x32_bf16 v[88:91], v[172:175], v[218:221], v[88:91]
	v_mfma_f32_16x16x32_bf16 v[84:87], v[180:183], v[218:221], v[84:87]
	v_mfma_f32_16x16x32_bf16 v[72:75], v[172:175], v[226:229], v[72:75]
	v_mfma_f32_16x16x32_bf16 v[68:71], v[180:183], v[226:229], v[68:71]
	s_barrier
	s_add_i32 s77, s83, s70
	v_lshl_add_u64 v[200:201], s[26:27], 0, v[146:147]
	s_mov_b32 m0, s77
	ds_read_b128 v[184:187], v159 offset:16384
	ds_read_b128 v[188:191], v159 offset:17408
	ds_read_b128 v[192:195], v159 offset:18432
	ds_read_b128 v[196:199], v159 offset:19456
	ds_read_b128 v[214:217], v159 offset:20480
	ds_read_b128 v[218:221], v159 offset:21504
	ds_read_b128 v[222:225], v159 offset:22528
	ds_read_b128 v[226:229], v159 offset:23552
	global_load_lds_dwordx4 v[200:201], off
	s_add_i32 m0, s77, 0x2000
	s_add_u32 s86, s26, 0xb0000
	v_lshl_add_u64 v[230:231], s[26:27], 0, v[148:149]
	s_addc_u32 s87, s27, 0
	s_add_i32 s68, s68, s70
	global_load_lds_dwordx4 v[230:231], off
	v_lshl_add_u64 v[232:233], s[86:87], 0, v[146:147]
	s_mov_b32 m0, s68
	v_lshl_add_u64 v[234:235], s[28:29], 0, v[148:149]
	global_load_lds_dwordx4 v[232:233], off
	v_lshl_add_u64 v[232:233], s[86:87], 0, v[148:149]
	s_add_i32 m0, s68, 0x2000
	s_nop 0
	global_load_lds_dwordx4 v[232:233], off
	v_lshl_add_u64 v[232:233], s[28:29], 0, v[146:147]
	s_mov_b32 m0, s71
	s_nop 0
	global_load_lds_dwordx4 v[232:233], off
	s_mov_b32 m0, s72
	s_nop 0
	global_load_lds_dwordx4 v[234:235], off
	s_waitcnt vmcnt(8)
	s_waitcnt lgkmcnt(0)
	s_barrier
; #define PG8_STAGE(bufoff, gbase, voff) do { _Pragma("unroll") for (int _i = 0; _i < 2; ++_i) \
;         __builtin_amdgcn_global_load_lds((const unsigned*)((const char*)(gbase) + (voff)[_i]), (LAS unsigned*)(lds + (bufoff) + ldsw + _i * 8192), 16, 0, 0); } while (0)
; #define PG8_LDA(dst, b, h) do { _Pragma("unroll") for (int m = 0; m < 4; ++m) _Pragma("unroll") for (int k = 0; k < 2; ++k) dst[m][k] = *(const LAS bf16x8*)(lds + PG8_SA(b, h) + aoff + m * 2048 + k * 1024); } while (0)
; #define PG8_LDB(dst, b, h) do { _Pragma("unroll") for (int n = 0; n < 2; ++n) _Pragma("unroll") for (int k = 0; k < 2; ++k) dst[n][k] = *(const LAS bf16x8*)(lds + PG8_SB(b, h) + boff + n * 2048 + k * 1024); } while (0)
; #define PG8_MMA(ai, bj, At, Bt) do { __builtin_amdgcn_s_setprio(1); _Pragma("unroll") for (int m = 0; m < 4; ++m) _Pragma("unroll") for (int n = 0; n < 2; ++n) _Pragma("unroll") for (int k = 0; k < 2; ++k) \
;         acc[ai][bj][m][n] = __builtin_amdgcn_mfma_f32_16x16x32_bf16(Bt[n][k], At[m][k], acc[ai][bj][m][n], 0, 0, 0); __builtin_amdgcn_s_setprio(0); } while (0)
; #define PG8_WAIT_V(n) asm volatile("s_waitcnt vmcnt(" #n ")" ::: "memory")
; #define PG8_WAIT_L(n) asm volatile("s_waitcnt lgkmcnt(" #n ")" ::: "memory")
; #define PG8_BAR __builtin_amdgcn_s_barrier()
; #define PG8_SCHED __builtin_amdgcn_sched_barrier(0)
; template <class Epi>
; __device__ __forceinline__ void gemm_phase(LAS unsigned char* lds, const Gemm g, const int G, const int cidx, const Epi& E) {
;     ...
;             PG8_WAIT_V(8); PG8_WAIT_L(0); PG8_BAR; PG8_MMA(1, 0, At, B0); PG8_MMA(1, 1, At, B1); PG8_BAR; PG8_SCHED;
;             PG8_LDB(B0, 1, 0); PG8_LDB(B1, 1, 1); PG8_SCHED; PG8_LDA(At, 1, 0); PG8_STAGE(PG8_SA(0, 1), a2 + hstep, voffA);
;             PG8_WAIT_V(8); PG8_WAIT_L(0); PG8_BAR; PG8_MMA(0, 0, At, B0); PG8_MMA(0, 1, At, B1); PG8_BAR; PG8_SCHED;
	s_waitcnt lgkmcnt(0)
	v_mfma_f32_16x16x32_bf16 v[64:67], v[132:135], v[184:187], v[64:67]
	v_mfma_f32_16x16x32_bf16 v[60:63], v[160:163], v[184:187], v[60:63]
	v_mfma_f32_16x16x32_bf16 v[48:51], v[132:135], v[192:195], v[48:51]
	v_mfma_f32_16x16x32_bf16 v[44:47], v[160:163], v[192:195], v[44:47]
	v_mfma_f32_16x16x32_bf16 v[32:35], v[132:135], v[214:217], v[32:35]
	v_mfma_f32_16x16x32_bf16 v[28:31], v[160:163], v[214:217], v[28:31]
	v_mfma_f32_16x16x32_bf16 v[16:19], v[132:135], v[222:225], v[16:19]
	v_mfma_f32_16x16x32_bf16 v[12:15], v[160:163], v[222:225], v[12:15]
	v_mfma_f32_16x16x32_bf16 v[64:67], v[140:143], v[188:191], v[64:67]
	v_mfma_f32_16x16x32_bf16 v[60:63], v[164:167], v[188:191], v[60:63]
	v_mfma_f32_16x16x32_bf16 v[48:51], v[140:143], v[196:199], v[48:51]
	v_mfma_f32_16x16x32_bf16 v[44:47], v[164:167], v[196:199], v[44:47]
	v_mfma_f32_16x16x32_bf16 v[32:35], v[140:143], v[218:221], v[32:35]
	v_mfma_f32_16x16x32_bf16 v[28:31], v[164:167], v[218:221], v[28:31]
	v_mfma_f32_16x16x32_bf16 v[16:19], v[140:143], v[226:229], v[16:19]
	v_mfma_f32_16x16x32_bf16 v[12:15], v[164:167], v[226:229], v[12:15]
	v_mfma_f32_16x16x32_bf16 v[56:59], v[168:171], v[184:187], v[56:59]
	v_mfma_f32_16x16x32_bf16 v[52:55], v[176:179], v[184:187], v[52:55]
	v_mfma_f32_16x16x32_bf16 v[40:43], v[168:171], v[192:195], v[40:43]
	v_mfma_f32_16x16x32_bf16 v[36:39], v[176:179], v[192:195], v[36:39]
	v_mfma_f32_16x16x32_bf16 v[24:27], v[168:171], v[214:217], v[24:27]
	v_mfma_f32_16x16x32_bf16 v[20:23], v[176:179], v[214:217], v[20:23]
	v_mfma_f32_16x16x32_bf16 v[8:11], v[168:171], v[222:225], v[8:11]
	v_mfma_f32_16x16x32_bf16 v[4:7], v[176:179], v[222:225], v[4:7]
	v_mfma_f32_16x16x32_bf16 v[56:59], v[172:175], v[188:191], v[56:59]
	v_mfma_f32_16x16x32_bf16 v[52:55], v[180:183], v[188:191], v[52:55]
	v_mfma_f32_16x16x32_bf16 v[40:43], v[172:175], v[196:199], v[40:43]
	v_mfma_f32_16x16x32_bf16 v[36:39], v[180:183], v[196:199], v[36:39]
	v_mfma_f32_16x16x32_bf16 v[24:27], v[172:175], v[218:221], v[24:27]
	v_mfma_f32_16x16x32_bf16 v[20:23], v[180:183], v[218:221], v[20:23]
	v_mfma_f32_16x16x32_bf16 v[8:11], v[172:175], v[226:229], v[8:11]
	v_mfma_f32_16x16x32_bf16 v[4:7], v[180:183], v[226:229], v[4:7]
	s_barrier
	s_add_i32 s68, 0, 0x18000
	v_add_u32_e32 v3, s68, v157
	s_add_i32 s77, 0, 0x1c000
	ds_read_b128 v[132:135], v3
	ds_read_b128 v[140:143], v3 offset:1024
	ds_read_b128 v[160:163], v3 offset:2048
	ds_read_b128 v[164:167], v3 offset:3072
	v_add_u32_e32 v3, s77, v157
	ds_read_b128 v[168:171], v3
	ds_read_b128 v[172:175], v3 offset:1024
	ds_read_b128 v[176:179], v3 offset:2048
	ds_read_b128 v[180:183], v3 offset:3072
	s_add_u32 s28, s28, 0xb0000
	s_addc_u32 s29, s29, 0
	s_mov_b32 m0, s73
	v_lshl_add_u64 v[236:237], s[28:29], 0, v[146:147]
	ds_read_b128 v[184:187], v159 offset:32768
	ds_read_b128 v[188:191], v159 offset:33792
	ds_read_b128 v[192:195], v159 offset:34816
	ds_read_b128 v[196:199], v159 offset:35840
	ds_read_b128 v[214:217], v159 offset:36864
	ds_read_b128 v[218:221], v159 offset:37888
	ds_read_b128 v[222:225], v159 offset:38912
	ds_read_b128 v[226:229], v159 offset:39936
	global_load_lds_dwordx4 v[236:237], off
	v_lshl_add_u64 v[236:237], s[28:29], 0, v[148:149]
	s_mov_b32 m0, s74
	s_nop 0
	global_load_lds_dwordx4 v[236:237], off
	s_waitcnt vmcnt(8)
	s_waitcnt lgkmcnt(0)
	s_barrier
	s_waitcnt lgkmcnt(0)
	v_mfma_f32_16x16x32_bf16 v[100:103], v[132:135], v[184:187], v[100:103]
	v_mfma_f32_16x16x32_bf16 v[108:111], v[160:163], v[184:187], v[108:111]
	v_mfma_f32_16x16x32_bf16 v[120:123], v[132:135], v[192:195], v[120:123]
	v_mfma_f32_16x16x32_bf16 v[128:131], v[160:163], v[192:195], v[128:131]
	v_mfma_f32_16x16x32_bf16 v[96:99], v[132:135], v[214:217], v[96:99]
	v_mfma_f32_16x16x32_bf16 v[92:95], v[160:163], v[214:217], v[92:95]
	v_mfma_f32_16x16x32_bf16 v[80:83], v[132:135], v[222:225], v[80:83]
	v_mfma_f32_16x16x32_bf16 v[76:79], v[160:163], v[222:225], v[76:79]
	v_mfma_f32_16x16x32_bf16 v[100:103], v[140:143], v[188:191], v[100:103]
	v_mfma_f32_16x16x32_bf16 v[108:111], v[164:167], v[188:191], v[108:111]
	v_mfma_f32_16x16x32_bf16 v[120:123], v[140:143], v[196:199], v[120:123]
	v_mfma_f32_16x16x32_bf16 v[128:131], v[164:167], v[196:199], v[128:131]
	v_mfma_f32_16x16x32_bf16 v[96:99], v[140:143], v[218:221], v[96:99]
	v_mfma_f32_16x16x32_bf16 v[92:95], v[164:167], v[218:221], v[92:95]
	v_mfma_f32_16x16x32_bf16 v[80:83], v[140:143], v[226:229], v[80:83]
	v_mfma_f32_16x16x32_bf16 v[76:79], v[164:167], v[226:229], v[76:79]
	v_mfma_f32_16x16x32_bf16 v[116:119], v[168:171], v[184:187], v[116:119]
	v_mfma_f32_16x16x32_bf16 v[124:127], v[176:179], v[184:187], v[124:127]
	v_mfma_f32_16x16x32_bf16 v[112:115], v[168:171], v[192:195], v[112:115]
	v_mfma_f32_16x16x32_bf16 v[104:107], v[176:179], v[192:195], v[104:107]
	v_mfma_f32_16x16x32_bf16 v[88:91], v[168:171], v[214:217], v[88:91]
	v_mfma_f32_16x16x32_bf16 v[84:87], v[176:179], v[214:217], v[84:87]
	v_mfma_f32_16x16x32_bf16 v[72:75], v[168:171], v[222:225], v[72:75]
	v_mfma_f32_16x16x32_bf16 v[68:71], v[176:179], v[222:225], v[68:71]
	v_mfma_f32_16x16x32_bf16 v[116:119], v[172:175], v[188:191], v[116:119]
	v_mfma_f32_16x16x32_bf16 v[124:127], v[180:183], v[188:191], v[124:127]
	v_mfma_f32_16x16x32_bf16 v[112:115], v[172:175], v[196:199], v[112:115]
	v_mfma_f32_16x16x32_bf16 v[104:107], v[180:183], v[196:199], v[104:107]
	v_mfma_f32_16x16x32_bf16 v[88:91], v[172:175], v[218:221], v[88:91]
	v_mfma_f32_16x16x32_bf16 v[84:87], v[180:183], v[218:221], v[84:87]
	v_mfma_f32_16x16x32_bf16 v[72:75], v[172:175], v[226:229], v[72:75]
	v_mfma_f32_16x16x32_bf16 v[68:71], v[180:183], v[226:229], v[68:71]
	s_barrier
; #define PG8_STAGE(bufoff, gbase, voff) do { _Pragma("unroll") for (int _i = 0; _i < 2; ++_i) \
;         __builtin_amdgcn_global_load_lds((const unsigned*)((const char*)(gbase) + (voff)[_i]), (LAS unsigned*)(lds + (bufoff) + ldsw + _i * 8192), 16, 0, 0); } while (0)
; #define PG8_LDA(dst, b, h) do { _Pragma("unroll") for (int m = 0; m < 4; ++m) _Pragma("unroll") for (int k = 0; k < 2; ++k) dst[m][k] = *(const LAS bf16x8*)(lds + PG8_SA(b, h) + aoff + m * 2048 + k * 1024); } while (0)
; #define PG8_MMA(ai, bj, At, Bt) do { __builtin_amdgcn_s_setprio(1); _Pragma("unroll") for (int m = 0; m < 4; ++m) _Pragma("unroll") for (int n = 0; n < 2; ++n) _Pragma("unroll") for (int k = 0; k < 2; ++k) \
;         acc[ai][bj][m][n] = __builtin_amdgcn_mfma_f32_16x16x32_bf16(Bt[n][k], At[m][k], acc[ai][bj][m][n], 0, 0, 0); __builtin_amdgcn_s_setprio(0); } while (0)
; #define PG8_WAIT_V(n) asm volatile("s_waitcnt vmcnt(" #n ")" ::: "memory")
; #define PG8_WAIT_L(n) asm volatile("s_waitcnt lgkmcnt(" #n ")" ::: "memory")
; #define PG8_BAR __builtin_amdgcn_s_barrier()
; #define PG8_SCHED __builtin_amdgcn_sched_barrier(0)
; template <class Epi>
; __device__ __forceinline__ void gemm_phase(LAS unsigned char* lds, const Gemm g, const int G, const int cidx, const Epi& E) {
;     ...
;             PG8_LDA(At, 1, 1); PG8_STAGE(PG8_SB(1, 0), b3, voffB); PG8_STAGE(PG8_SB(1, 1), b3 + hstep, voffB); PG8_STAGE(PG8_SA(1, 0), a3, voffA);
;             PG8_WAIT_V(8); PG8_WAIT_L(0); PG8_BAR; PG8_MMA(1, 0, At, B0); PG8_MMA(1, 1, At, B1); PG8_BAR; PG8_SCHED;
;         }
;         if constexpr (!Epi::AFTER_DRAIN) E(acc, cur, wr, wc, fr, fq);
;         if (!has_next) break;
; #pragma unroll
;         for (int a = 0; a < 2; ++a)
; #pragma unroll
;             for (int b = 0; b < 2; ++b)
; #pragma unroll
;                 for (int m = 0; m < 4; ++m)
; #pragma unroll
;                     for (int n = 0; n < 2; ++n) acc[a][b][m][n] = ZERO4;
;         cur = nxt; cA = nA; cB = nB; ++ui;
	s_add_i32 s28, s68, s70
	v_lshl_add_u64 v[200:201], v[200:201], 0, s[46:47]
	s_mov_b32 m0, s28
	ds_read_b128 v[184:187], v159 offset:49152
	ds_read_b128 v[188:191], v159 offset:50176
	ds_read_b128 v[192:195], v159 offset:51200
	ds_read_b128 v[196:199], v159 offset:52224
	ds_read_b128 v[214:217], v159 offset:53248
	ds_read_b128 v[218:221], v159 offset:54272
	ds_read_b128 v[222:225], v159 offset:55296
	ds_read_b128 v[226:229], v159 offset:56320
	global_load_lds_dwordx4 v[200:201], off
	s_add_i32 m0, s28, 0x2000
	s_add_u32 s26, s26, 0xb0080
	v_lshl_add_u64 v[200:201], v[230:231], 0, s[46:47]
	s_addc_u32 s27, s27, 0
	s_add_i32 s28, s77, s70
	global_load_lds_dwordx4 v[200:201], off
	v_lshl_add_u64 v[200:201], s[26:27], 0, v[146:147]
	s_mov_b32 m0, s28
	s_nop 0
	global_load_lds_dwordx4 v[200:201], off
	v_lshl_add_u64 v[200:201], s[26:27], 0, v[148:149]
	s_add_i32 m0, s28, 0x2000
	s_nop 0
	global_load_lds_dwordx4 v[200:201], off
	v_lshl_add_u64 v[200:201], v[232:233], 0, s[46:47]
	s_mov_b32 m0, s75
	s_nop 0
	global_load_lds_dwordx4 v[200:201], off
	v_lshl_add_u64 v[200:201], v[234:235], 0, s[46:47]
	s_mov_b32 m0, s76
	s_nop 0
	global_load_lds_dwordx4 v[200:201], off
	s_waitcnt vmcnt(8)
	s_waitcnt lgkmcnt(0)
	s_barrier
	s_waitcnt lgkmcnt(0)
	v_mfma_f32_16x16x32_bf16 v[64:67], v[132:135], v[184:187], v[64:67]
	v_mfma_f32_16x16x32_bf16 v[60:63], v[160:163], v[184:187], v[60:63]
	v_mfma_f32_16x16x32_bf16 v[48:51], v[132:135], v[192:195], v[48:51]
	v_mfma_f32_16x16x32_bf16 v[44:47], v[160:163], v[192:195], v[44:47]
	v_mfma_f32_16x16x32_bf16 v[32:35], v[132:135], v[214:217], v[32:35]
	v_mfma_f32_16x16x32_bf16 v[28:31], v[160:163], v[214:217], v[28:31]
	v_mfma_f32_16x16x32_bf16 v[16:19], v[132:135], v[222:225], v[16:19]
	v_mfma_f32_16x16x32_bf16 v[12:15], v[160:163], v[222:225], v[12:15]
	v_mfma_f32_16x16x32_bf16 v[64:67], v[140:143], v[188:191], v[64:67]
	v_mfma_f32_16x16x32_bf16 v[60:63], v[164:167], v[188:191], v[60:63]
	v_mfma_f32_16x16x32_bf16 v[48:51], v[140:143], v[196:199], v[48:51]
	v_mfma_f32_16x16x32_bf16 v[44:47], v[164:167], v[196:199], v[44:47]
	v_mfma_f32_16x16x32_bf16 v[32:35], v[140:143], v[218:221], v[32:35]
	v_mfma_f32_16x16x32_bf16 v[28:31], v[164:167], v[218:221], v[28:31]
	v_mfma_f32_16x16x32_bf16 v[16:19], v[140:143], v[226:229], v[16:19]
	v_mfma_f32_16x16x32_bf16 v[12:15], v[164:167], v[226:229], v[12:15]
	v_mfma_f32_16x16x32_bf16 v[56:59], v[168:171], v[184:187], v[56:59]
	v_mfma_f32_16x16x32_bf16 v[52:55], v[176:179], v[184:187], v[52:55]
	v_mfma_f32_16x16x32_bf16 v[40:43], v[168:171], v[192:195], v[40:43]
	v_mfma_f32_16x16x32_bf16 v[36:39], v[176:179], v[192:195], v[36:39]
	v_mfma_f32_16x16x32_bf16 v[24:27], v[168:171], v[214:217], v[24:27]
	v_mfma_f32_16x16x32_bf16 v[20:23], v[176:179], v[214:217], v[20:23]
	v_mfma_f32_16x16x32_bf16 v[8:11], v[168:171], v[222:225], v[8:11]
	v_mfma_f32_16x16x32_bf16 v[4:7], v[176:179], v[222:225], v[4:7]
	v_mfma_f32_16x16x32_bf16 v[56:59], v[172:175], v[188:191], v[56:59]
	v_mfma_f32_16x16x32_bf16 v[52:55], v[180:183], v[188:191], v[52:55]
	v_mfma_f32_16x16x32_bf16 v[40:43], v[172:175], v[196:199], v[40:43]
	v_mfma_f32_16x16x32_bf16 v[36:39], v[180:183], v[196:199], v[36:39]
	v_mfma_f32_16x16x32_bf16 v[24:27], v[172:175], v[218:221], v[24:27]
	v_mfma_f32_16x16x32_bf16 v[20:23], v[180:183], v[218:221], v[20:23]
	v_mfma_f32_16x16x32_bf16 v[8:11], v[172:175], v[226:229], v[8:11]
	v_mfma_f32_16x16x32_bf16 v[4:7], v[180:183], v[226:229], v[4:7]
	s_add_i32 s45, s45, 2
	s_add_u32 s24, s24, 0x100
	s_addc_u32 s25, s25, 0
	s_cmp_gt_u32 s45, 41
	s_barrier
	s_cbranch_scc0 .LBB0_450
	s_add_u32 s24, s43, 0xffffff00
	s_addc_u32 s25, s44, -1
	s_and_b64 vcc, exec, s[6:7]
	s_cbranch_vccnz .LBB0_453
	v_mov_b32_e32 v4, 0
	s_mov_b32 s14, s84
	s_mov_b32 s35, s88
	s_mov_b64 s[10:11], s[20:21]
	s_mov_b32 s79, s33
	v_mov_b32_e32 v5, v4
	v_mov_b32_e32 v6, v4
	v_mov_b32_e32 v7, v4
	v_mov_b32_e32 v8, v4
	v_mov_b32_e32 v9, v4
	v_mov_b32_e32 v10, v4
	v_mov_b32_e32 v11, v4
	v_mov_b32_e32 v20, v4
	v_mov_b32_e32 v21, v4
	v_mov_b32_e32 v22, v4
	v_mov_b32_e32 v23, v4
	v_mov_b32_e32 v24, v4
	v_mov_b32_e32 v25, v4
	v_mov_b32_e32 v26, v4
	v_mov_b32_e32 v27, v4
	v_mov_b32_e32 v36, v4
	v_mov_b32_e32 v37, v4
	v_mov_b32_e32 v38, v4
	v_mov_b32_e32 v39, v4
	v_mov_b32_e32 v40, v4
	v_mov_b32_e32 v41, v4
	v_mov_b32_e32 v42, v4
	v_mov_b32_e32 v43, v4
	v_mov_b32_e32 v52, v4
	v_mov_b32_e32 v53, v4
	v_mov_b32_e32 v54, v4
	v_mov_b32_e32 v55, v4
	v_mov_b32_e32 v56, v4
	v_mov_b32_e32 v57, v4
	v_mov_b32_e32 v58, v4
	v_mov_b32_e32 v59, v4
	v_mov_b32_e32 v12, v4
	v_mov_b32_e32 v13, v4
	v_mov_b32_e32 v14, v4
	v_mov_b32_e32 v15, v4
	v_mov_b32_e32 v16, v4
	v_mov_b32_e32 v17, v4
	v_mov_b32_e32 v18, v4
	v_mov_b32_e32 v19, v4
	v_mov_b32_e32 v28, v4
	v_mov_b32_e32 v29, v4
	v_mov_b32_e32 v30, v4
	v_mov_b32_e32 v31, v4
	v_mov_b32_e32 v32, v4
	v_mov_b32_e32 v33, v4
	v_mov_b32_e32 v34, v4
	v_mov_b32_e32 v35, v4
	v_mov_b32_e32 v44, v4
	v_mov_b32_e32 v45, v4
	v_mov_b32_e32 v46, v4
	v_mov_b32_e32 v47, v4
	v_mov_b32_e32 v48, v4
	v_mov_b32_e32 v49, v4
	v_mov_b32_e32 v50, v4
	v_mov_b32_e32 v51, v4
	v_mov_b32_e32 v60, v4
	v_mov_b32_e32 v61, v4
	v_mov_b32_e32 v62, v4
	v_mov_b32_e32 v63, v4
	v_mov_b32_e32 v64, v4
	v_mov_b32_e32 v65, v4
	v_mov_b32_e32 v66, v4
	v_mov_b32_e32 v67, v4
	v_mov_b32_e32 v68, v4
	v_mov_b32_e32 v69, v4
	v_mov_b32_e32 v70, v4
	v_mov_b32_e32 v71, v4
	v_mov_b32_e32 v72, v4
	v_mov_b32_e32 v73, v4
	v_mov_b32_e32 v74, v4
	v_mov_b32_e32 v75, v4
	v_mov_b32_e32 v84, v4
	v_mov_b32_e32 v85, v4
	v_mov_b32_e32 v86, v4
	v_mov_b32_e32 v87, v4
	v_mov_b32_e32 v88, v4
	v_mov_b32_e32 v89, v4
	v_mov_b32_e32 v90, v4
	v_mov_b32_e32 v91, v4
	v_mov_b32_e32 v104, v4
	v_mov_b32_e32 v105, v4
	v_mov_b32_e32 v106, v4
	v_mov_b32_e32 v107, v4
	v_mov_b32_e32 v112, v4
	v_mov_b32_e32 v113, v4
	v_mov_b32_e32 v114, v4
	v_mov_b32_e32 v115, v4
	v_mov_b32_e32 v124, v4
	v_mov_b32_e32 v125, v4
	v_mov_b32_e32 v126, v4
	v_mov_b32_e32 v127, v4
	v_mov_b32_e32 v116, v4
	v_mov_b32_e32 v117, v4
	v_mov_b32_e32 v118, v4
	v_mov_b32_e32 v119, v4
	v_mov_b32_e32 v76, v4
	v_mov_b32_e32 v77, v4
	v_mov_b32_e32 v78, v4
	v_mov_b32_e32 v79, v4
	v_mov_b32_e32 v80, v4
	v_mov_b32_e32 v81, v4
	v_mov_b32_e32 v82, v4
	v_mov_b32_e32 v83, v4
	v_mov_b32_e32 v92, v4
	v_mov_b32_e32 v93, v4
	v_mov_b32_e32 v94, v4
	v_mov_b32_e32 v95, v4
	v_mov_b32_e32 v96, v4
	v_mov_b32_e32 v97, v4
	v_mov_b32_e32 v98, v4
	v_mov_b32_e32 v99, v4
	v_mov_b32_e32 v128, v4
	v_mov_b32_e32 v129, v4
	v_mov_b32_e32 v130, v4
	v_mov_b32_e32 v131, v4
	v_mov_b32_e32 v120, v4
	v_mov_b32_e32 v121, v4
	v_mov_b32_e32 v122, v4
	v_mov_b32_e32 v123, v4
	v_mov_b32_e32 v108, v4
	v_mov_b32_e32 v109, v4
	v_mov_b32_e32 v110, v4
	v_mov_b32_e32 v111, v4
	v_mov_b32_e32 v100, v4
	v_mov_b32_e32 v101, v4
	v_mov_b32_e32 v102, v4
	v_mov_b32_e32 v103, v4
	s_mov_b32 s83, 0x18000
	s_mov_b32 s86, 0x3fb8aa3b
	s_andn2_b64 vcc, exec, s[4:5]
	s_cbranch_vccnz .LBB0_454
	s_branch .LBB0_455

; #define PG8_STAGE(bufoff, gbase, voff) do { _Pragma("unroll") for (int _i = 0; _i < 2; ++_i) \
;         __builtin_amdgcn_global_load_lds((const unsigned*)((const char*)(gbase) + (voff)[_i]), (LAS unsigned*)(lds + (bufoff) + ldsw + _i * 8192), 16, 0, 0); } while (0)
; #define PG8_LDA(dst, b, h) do { _Pragma("unroll") for (int m = 0; m < 4; ++m) _Pragma("unroll") for (int k = 0; k < 2; ++k) dst[m][k] = *(const LAS bf16x8*)(lds + PG8_SA(b, h) + aoff + m * 2048 + k * 1024); } while (0)
; #define PG8_LDB(dst, b, h) do { _Pragma("unroll") for (int n = 0; n < 2; ++n) _Pragma("unroll") for (int k = 0; k < 2; ++k) dst[n][k] = *(const LAS bf16x8*)(lds + PG8_SB(b, h) + boff + n * 2048 + k * 1024); } while (0)
; #define PG8_MMA(ai, bj, At, Bt) do { __builtin_amdgcn_s_setprio(1); _Pragma("unroll") for (int m = 0; m < 4; ++m) _Pragma("unroll") for (int n = 0; n < 2; ++n) _Pragma("unroll") for (int k = 0; k < 2; ++k) \
;         acc[ai][bj][m][n] = __builtin_amdgcn_mfma_f32_16x16x32_bf16(Bt[n][k], At[m][k], acc[ai][bj][m][n], 0, 0, 0); __builtin_amdgcn_s_setprio(0); } while (0)
; #define PG8_WAIT_V(n) asm volatile("s_waitcnt vmcnt(" #n ")" ::: "memory")
; #define PG8_WAIT_L(n) asm volatile("s_waitcnt lgkmcnt(" #n ")" ::: "memory")
; #define PG8_BAR __builtin_amdgcn_s_barrier()
; #define PG8_SCHED __builtin_amdgcn_sched_barrier(0)
; template <class Epi>
; __device__ __forceinline__ void gemm_phase(LAS unsigned char* lds, const Gemm g, const int G, const int cidx, const Epi& E) {
;     ...
;         for (int t = 0; t < nt; t += 2) {
;             const bool last = (t == nt - 2);
;             const char* a1 = cA + (size_t)(t + 1) * kstep;
;             const char* a2 = last ? nA : cA + (size_t)(t + 2) * kstep; const char* b2 = last ? nB : cB + (size_t)(t + 2) * kstep;
;             const char* a3 = a2 + kstep; const char* b3 = b2 + kstep;
;             PG8_LDB(B0, 0, 0); PG8_LDB(B1, 0, 1); PG8_SCHED; PG8_LDA(At, 0, 0); PG8_STAGE(PG8_SA(1, 1), a1 + hstep, voffA);
;             PG8_WAIT_V(8); PG8_WAIT_L(0); PG8_BAR; PG8_MMA(0, 0, At, B0); PG8_MMA(0, 1, At, B1); PG8_BAR; PG8_SCHED;
;             PG8_LDA(At, 0, 1); PG8_STAGE(PG8_SB(0, 0), b2, voffB); PG8_STAGE(PG8_SB(0, 1), b2 + hstep, voffB); PG8_STAGE(PG8_SA(0, 0), a2, voffA);
;             PG8_WAIT_V(8); PG8_WAIT_L(0); PG8_BAR; PG8_MMA(1, 0, At, B0); PG8_MMA(1, 1, At, B1); PG8_BAR; PG8_SCHED;
.LBB0_601:
	s_add_i32 s43, 0, 0x10000
	v_add_u32_e32 v132, s43, v145
	ds_read_b128 v[158:161], v132
	ds_read_b128 v[164:167], v132 offset:1024
	ds_read_b128 v[168:171], v132 offset:2048
	ds_read_b128 v[172:175], v132 offset:3072
	s_add_i32 s68, 0, 0x14000
	v_add_u32_e32 v132, s68, v145
	ds_read_b128 v[176:179], v132
	ds_read_b128 v[180:183], v132 offset:1024
	ds_read_b128 v[184:187], v132 offset:2048
	ds_read_b128 v[188:191], v132 offset:3072
	v_lshl_add_u64 v[132:133], s[20:21], 0, v[156:157]
	s_add_i32 m0, s97, 0xc000
	ds_read_b128 v[192:195], v163
	ds_read_b128 v[196:199], v163 offset:1024
	ds_read_b128 v[214:217], v163 offset:2048
	ds_read_b128 v[218:221], v163 offset:3072
	ds_read_b128 v[222:225], v163 offset:4096
	ds_read_b128 v[226:229], v163 offset:5120
	ds_read_b128 v[230:233], v163 offset:6144
	ds_read_b128 v[234:237], v163 offset:7168
	s_add_u32 s24, s20, 0xfffc0080
	s_addc_u32 s25, s21, -1
	s_cmp_eq_u32 s45, 12
	s_cselect_b32 s27, s11, s25
	s_cselect_b32 s26, s19, s24
	s_cselect_b32 s25, s9, s44
	s_cselect_b32 s24, s33, s42
	global_load_lds_dwordx4 v[132:133], off
	v_lshl_add_u64 v[132:133], s[20:21], 0, v[154:155]
	s_add_i32 m0, s97, 0xe000
	s_nop 0
	global_load_lds_dwordx4 v[132:133], off
	s_waitcnt vmcnt(8)
	s_waitcnt lgkmcnt(0)
	s_barrier
	s_waitcnt lgkmcnt(0)
	v_mfma_f32_16x16x32_bf16 v[128:131], v[158:161], v[192:195], v[128:131]
	v_mfma_f32_16x16x32_bf16 v[124:127], v[168:171], v[192:195], v[124:127]
	v_mfma_f32_16x16x32_bf16 v[120:123], v[158:161], v[214:217], v[120:123]
	v_mfma_f32_16x16x32_bf16 v[112:115], v[168:171], v[214:217], v[112:115]
	v_mfma_f32_16x16x32_bf16 v[104:107], v[158:161], v[222:225], v[104:107]
	v_mfma_f32_16x16x32_bf16 v[96:99], v[168:171], v[222:225], v[96:99]
	v_mfma_f32_16x16x32_bf16 v[88:91], v[158:161], v[230:233], v[88:91]
	v_mfma_f32_16x16x32_bf16 v[80:83], v[168:171], v[230:233], v[80:83]
	v_mfma_f32_16x16x32_bf16 v[128:131], v[164:167], v[196:199], v[128:131]
	v_mfma_f32_16x16x32_bf16 v[124:127], v[172:175], v[196:199], v[124:127]
	v_mfma_f32_16x16x32_bf16 v[120:123], v[164:167], v[218:221], v[120:123]
	v_mfma_f32_16x16x32_bf16 v[112:115], v[172:175], v[218:221], v[112:115]
	v_mfma_f32_16x16x32_bf16 v[104:107], v[164:167], v[226:229], v[104:107]
	v_mfma_f32_16x16x32_bf16 v[96:99], v[172:175], v[226:229], v[96:99]
	v_mfma_f32_16x16x32_bf16 v[88:91], v[164:167], v[234:237], v[88:91]
	v_mfma_f32_16x16x32_bf16 v[80:83], v[172:175], v[234:237], v[80:83]
	v_mfma_f32_16x16x32_bf16 v[116:119], v[176:179], v[192:195], v[116:119]
	v_mfma_f32_16x16x32_bf16 v[108:111], v[184:187], v[192:195], v[108:111]
	v_mfma_f32_16x16x32_bf16 v[100:103], v[176:179], v[214:217], v[100:103]
	v_mfma_f32_16x16x32_bf16 v[92:95], v[184:187], v[214:217], v[92:95]
	v_mfma_f32_16x16x32_bf16 v[84:87], v[176:179], v[222:225], v[84:87]
	v_mfma_f32_16x16x32_bf16 v[76:79], v[184:187], v[222:225], v[76:79]
	v_mfma_f32_16x16x32_bf16 v[72:75], v[176:179], v[230:233], v[72:75]
	v_mfma_f32_16x16x32_bf16 v[68:71], v[184:187], v[230:233], v[68:71]
	v_mfma_f32_16x16x32_bf16 v[116:119], v[180:183], v[196:199], v[116:119]
	v_mfma_f32_16x16x32_bf16 v[108:111], v[188:191], v[196:199], v[108:111]
	v_mfma_f32_16x16x32_bf16 v[100:103], v[180:183], v[218:221], v[100:103]
	v_mfma_f32_16x16x32_bf16 v[92:95], v[188:191], v[218:221], v[92:95]
	v_mfma_f32_16x16x32_bf16 v[84:87], v[180:183], v[226:229], v[84:87]
	v_mfma_f32_16x16x32_bf16 v[76:79], v[188:191], v[226:229], v[76:79]
	v_mfma_f32_16x16x32_bf16 v[72:75], v[180:183], v[234:237], v[72:75]
	v_mfma_f32_16x16x32_bf16 v[68:71], v[188:191], v[234:237], v[68:71]
	s_barrier
	s_add_i32 s43, s43, s95
	v_lshl_add_u64 v[132:133], s[24:25], 0, v[148:149]
	s_mov_b32 m0, s43
	ds_read_b128 v[192:195], v163 offset:16384
	ds_read_b128 v[196:199], v163 offset:17408
	ds_read_b128 v[214:217], v163 offset:18432
	ds_read_b128 v[218:221], v163 offset:19456
	ds_read_b128 v[222:225], v163 offset:20480
	ds_read_b128 v[226:229], v163 offset:21504
	ds_read_b128 v[230:233], v163 offset:22528
	ds_read_b128 v[234:237], v163 offset:23552
	global_load_lds_dwordx4 v[132:133], off
	s_add_i32 m0, s43, 0x2000
	s_add_u32 s86, s24, 0x40000
	v_lshl_add_u64 v[134:135], s[24:25], 0, v[0:1]
	s_addc_u32 s87, s25, 0
	s_add_i32 s43, s68, s95
	global_load_lds_dwordx4 v[134:135], off
	v_lshl_add_u64 v[140:141], s[86:87], 0, v[148:149]
	s_mov_b32 m0, s43
	v_lshl_add_u64 v[142:143], s[26:27], 0, v[146:147]
	global_load_lds_dwordx4 v[140:141], off
	v_lshl_add_u64 v[140:141], s[86:87], 0, v[0:1]
	s_add_i32 m0, s43, 0x2000
	s_nop 0
	global_load_lds_dwordx4 v[140:141], off
	v_lshl_add_u64 v[140:141], s[26:27], 0, v[150:151]
	s_mov_b32 m0, s97
	s_nop 0
	global_load_lds_dwordx4 v[140:141], off
	s_mov_b32 m0, s22
	s_nop 0
	global_load_lds_dwordx4 v[142:143], off
	s_waitcnt vmcnt(8)
	s_waitcnt lgkmcnt(0)
	s_barrier
; #define PG8_STAGE(bufoff, gbase, voff) do { _Pragma("unroll") for (int _i = 0; _i < 2; ++_i) \
;         __builtin_amdgcn_global_load_lds((const unsigned*)((const char*)(gbase) + (voff)[_i]), (LAS unsigned*)(lds + (bufoff) + ldsw + _i * 8192), 16, 0, 0); } while (0)
; #define PG8_LDA(dst, b, h) do { _Pragma("unroll") for (int m = 0; m < 4; ++m) _Pragma("unroll") for (int k = 0; k < 2; ++k) dst[m][k] = *(const LAS bf16x8*)(lds + PG8_SA(b, h) + aoff + m * 2048 + k * 1024); } while (0)
; #define PG8_LDB(dst, b, h) do { _Pragma("unroll") for (int n = 0; n < 2; ++n) _Pragma("unroll") for (int k = 0; k < 2; ++k) dst[n][k] = *(const LAS bf16x8*)(lds + PG8_SB(b, h) + boff + n * 2048 + k * 1024); } while (0)
; #define PG8_MMA(ai, bj, At, Bt) do { __builtin_amdgcn_s_setprio(1); _Pragma("unroll") for (int m = 0; m < 4; ++m) _Pragma("unroll") for (int n = 0; n < 2; ++n) _Pragma("unroll") for (int k = 0; k < 2; ++k) \
;         acc[ai][bj][m][n] = __builtin_amdgcn_mfma_f32_16x16x32_bf16(Bt[n][k], At[m][k], acc[ai][bj][m][n], 0, 0, 0); __builtin_amdgcn_s_setprio(0); } while (0)
; #define PG8_WAIT_V(n) asm volatile("s_waitcnt vmcnt(" #n ")" ::: "memory")
; #define PG8_WAIT_L(n) asm volatile("s_waitcnt lgkmcnt(" #n ")" ::: "memory")
; #define PG8_BAR __builtin_amdgcn_s_barrier()
; #define PG8_SCHED __builtin_amdgcn_sched_barrier(0)
; template <class Epi>
; __device__ __forceinline__ void gemm_phase(LAS unsigned char* lds, const Gemm g, const int G, const int cidx, const Epi& E) {
;     ...
;             PG8_WAIT_V(8); PG8_WAIT_L(0); PG8_BAR; PG8_MMA(1, 0, At, B0); PG8_MMA(1, 1, At, B1); PG8_BAR; PG8_SCHED;
;             PG8_LDB(B0, 1, 0); PG8_LDB(B1, 1, 1); PG8_SCHED; PG8_LDA(At, 1, 0); PG8_STAGE(PG8_SA(0, 1), a2 + hstep, voffA);
;             PG8_WAIT_V(8); PG8_WAIT_L(0); PG8_BAR; PG8_MMA(0, 0, At, B0); PG8_MMA(0, 1, At, B1); PG8_BAR; PG8_SCHED;
	s_waitcnt lgkmcnt(0)
	v_mfma_f32_16x16x32_bf16 v[64:67], v[158:161], v[192:195], v[64:67]
	v_mfma_f32_16x16x32_bf16 v[60:63], v[168:171], v[192:195], v[60:63]
	v_mfma_f32_16x16x32_bf16 v[56:59], v[158:161], v[214:217], v[56:59]
	v_mfma_f32_16x16x32_bf16 v[48:51], v[168:171], v[214:217], v[48:51]
	v_mfma_f32_16x16x32_bf16 v[40:43], v[158:161], v[222:225], v[40:43]
	v_mfma_f32_16x16x32_bf16 v[32:35], v[168:171], v[222:225], v[32:35]
	v_mfma_f32_16x16x32_bf16 v[24:27], v[158:161], v[230:233], v[24:27]
	v_mfma_f32_16x16x32_bf16 v[16:19], v[168:171], v[230:233], v[16:19]
	v_mfma_f32_16x16x32_bf16 v[64:67], v[164:167], v[196:199], v[64:67]
	v_mfma_f32_16x16x32_bf16 v[60:63], v[172:175], v[196:199], v[60:63]
	v_mfma_f32_16x16x32_bf16 v[56:59], v[164:167], v[218:221], v[56:59]
	v_mfma_f32_16x16x32_bf16 v[48:51], v[172:175], v[218:221], v[48:51]
	v_mfma_f32_16x16x32_bf16 v[40:43], v[164:167], v[226:229], v[40:43]
	v_mfma_f32_16x16x32_bf16 v[32:35], v[172:175], v[226:229], v[32:35]
	v_mfma_f32_16x16x32_bf16 v[24:27], v[164:167], v[234:237], v[24:27]
	v_mfma_f32_16x16x32_bf16 v[16:19], v[172:175], v[234:237], v[16:19]
	v_mfma_f32_16x16x32_bf16 v[52:55], v[176:179], v[192:195], v[52:55]
	v_mfma_f32_16x16x32_bf16 v[44:47], v[184:187], v[192:195], v[44:47]
	v_mfma_f32_16x16x32_bf16 v[36:39], v[176:179], v[214:217], v[36:39]
	v_mfma_f32_16x16x32_bf16 v[28:31], v[184:187], v[214:217], v[28:31]
	v_mfma_f32_16x16x32_bf16 v[20:23], v[176:179], v[222:225], v[20:23]
	v_mfma_f32_16x16x32_bf16 v[12:15], v[184:187], v[222:225], v[12:15]
	v_mfma_f32_16x16x32_bf16 v[8:11], v[176:179], v[230:233], v[8:11]
	v_mfma_f32_16x16x32_bf16 v[4:7], v[184:187], v[230:233], v[4:7]
	v_mfma_f32_16x16x32_bf16 v[52:55], v[180:183], v[196:199], v[52:55]
	v_mfma_f32_16x16x32_bf16 v[44:47], v[188:191], v[196:199], v[44:47]
	v_mfma_f32_16x16x32_bf16 v[36:39], v[180:183], v[218:221], v[36:39]
	v_mfma_f32_16x16x32_bf16 v[28:31], v[188:191], v[218:221], v[28:31]
	v_mfma_f32_16x16x32_bf16 v[20:23], v[180:183], v[226:229], v[20:23]
	v_mfma_f32_16x16x32_bf16 v[12:15], v[188:191], v[226:229], v[12:15]
	v_mfma_f32_16x16x32_bf16 v[8:11], v[180:183], v[234:237], v[8:11]
	v_mfma_f32_16x16x32_bf16 v[4:7], v[188:191], v[234:237], v[4:7]
	s_barrier
	s_add_i32 s43, 0, 0x18000
	s_add_i32 s68, 0, 0x1c000
	v_add_u32_e32 v172, s43, v145
	v_add_u32_e32 v188, s68, v145
	ds_read_b128 v[158:161], v172
	ds_read_b128 v[164:167], v172 offset:1024
	ds_read_b128 v[168:171], v172 offset:2048
	ds_read_b128 v[172:175], v172 offset:3072
	ds_read_b128 v[176:179], v188
	ds_read_b128 v[180:183], v188 offset:1024
	ds_read_b128 v[184:187], v188 offset:2048
	ds_read_b128 v[188:191], v188 offset:3072
	s_add_u32 s26, s26, 0x40000
	s_addc_u32 s27, s27, 0
	s_mov_b32 m0, s16
	v_lshl_add_u64 v[200:201], s[26:27], 0, v[150:151]
	ds_read_b128 v[192:195], v163 offset:32768
	ds_read_b128 v[196:199], v163 offset:33792
	ds_read_b128 v[214:217], v163 offset:34816
	ds_read_b128 v[218:221], v163 offset:35840
	ds_read_b128 v[222:225], v163 offset:36864
	ds_read_b128 v[226:229], v163 offset:37888
	ds_read_b128 v[230:233], v163 offset:38912
	ds_read_b128 v[234:237], v163 offset:39936
	global_load_lds_dwordx4 v[200:201], off
	v_lshl_add_u64 v[200:201], s[26:27], 0, v[146:147]
	s_mov_b32 m0, s17
	s_nop 0
	global_load_lds_dwordx4 v[200:201], off
	s_waitcnt vmcnt(8)
	s_waitcnt lgkmcnt(0)
	s_barrier
	s_waitcnt lgkmcnt(0)
	v_mfma_f32_16x16x32_bf16 v[128:131], v[158:161], v[192:195], v[128:131]
	v_mfma_f32_16x16x32_bf16 v[124:127], v[168:171], v[192:195], v[124:127]
	v_mfma_f32_16x16x32_bf16 v[120:123], v[158:161], v[214:217], v[120:123]
	v_mfma_f32_16x16x32_bf16 v[112:115], v[168:171], v[214:217], v[112:115]
	v_mfma_f32_16x16x32_bf16 v[104:107], v[158:161], v[222:225], v[104:107]
	v_mfma_f32_16x16x32_bf16 v[96:99], v[168:171], v[222:225], v[96:99]
	v_mfma_f32_16x16x32_bf16 v[88:91], v[158:161], v[230:233], v[88:91]
	v_mfma_f32_16x16x32_bf16 v[80:83], v[168:171], v[230:233], v[80:83]
	v_mfma_f32_16x16x32_bf16 v[128:131], v[164:167], v[196:199], v[128:131]
	v_mfma_f32_16x16x32_bf16 v[124:127], v[172:175], v[196:199], v[124:127]
	v_mfma_f32_16x16x32_bf16 v[120:123], v[164:167], v[218:221], v[120:123]
	v_mfma_f32_16x16x32_bf16 v[112:115], v[172:175], v[218:221], v[112:115]
	v_mfma_f32_16x16x32_bf16 v[104:107], v[164:167], v[226:229], v[104:107]
	v_mfma_f32_16x16x32_bf16 v[96:99], v[172:175], v[226:229], v[96:99]
	v_mfma_f32_16x16x32_bf16 v[88:91], v[164:167], v[234:237], v[88:91]
	v_mfma_f32_16x16x32_bf16 v[80:83], v[172:175], v[234:237], v[80:83]
	v_mfma_f32_16x16x32_bf16 v[116:119], v[176:179], v[192:195], v[116:119]
	v_mfma_f32_16x16x32_bf16 v[108:111], v[184:187], v[192:195], v[108:111]
	v_mfma_f32_16x16x32_bf16 v[100:103], v[176:179], v[214:217], v[100:103]
	v_mfma_f32_16x16x32_bf16 v[92:95], v[184:187], v[214:217], v[92:95]
	v_mfma_f32_16x16x32_bf16 v[84:87], v[176:179], v[222:225], v[84:87]
	v_mfma_f32_16x16x32_bf16 v[76:79], v[184:187], v[222:225], v[76:79]
	v_mfma_f32_16x16x32_bf16 v[72:75], v[176:179], v[230:233], v[72:75]
	v_mfma_f32_16x16x32_bf16 v[68:71], v[184:187], v[230:233], v[68:71]
	v_mfma_f32_16x16x32_bf16 v[116:119], v[180:183], v[196:199], v[116:119]
	v_mfma_f32_16x16x32_bf16 v[108:111], v[188:191], v[196:199], v[108:111]
	v_mfma_f32_16x16x32_bf16 v[100:103], v[180:183], v[218:221], v[100:103]
	v_mfma_f32_16x16x32_bf16 v[92:95], v[188:191], v[218:221], v[92:95]
	v_mfma_f32_16x16x32_bf16 v[84:87], v[180:183], v[226:229], v[84:87]
	v_mfma_f32_16x16x32_bf16 v[76:79], v[188:191], v[226:229], v[76:79]
	v_mfma_f32_16x16x32_bf16 v[72:75], v[180:183], v[234:237], v[72:75]
	v_mfma_f32_16x16x32_bf16 v[68:71], v[188:191], v[234:237], v[68:71]
	s_barrier
; #define PG8_STAGE(bufoff, gbase, voff) do { _Pragma("unroll") for (int _i = 0; _i < 2; ++_i) \
;         __builtin_amdgcn_global_load_lds((const unsigned*)((const char*)(gbase) + (voff)[_i]), (LAS unsigned*)(lds + (bufoff) + ldsw + _i * 8192), 16, 0, 0); } while (0)
; #define PG8_LDA(dst, b, h) do { _Pragma("unroll") for (int m = 0; m < 4; ++m) _Pragma("unroll") for (int k = 0; k < 2; ++k) dst[m][k] = *(const LAS bf16x8*)(lds + PG8_SA(b, h) + aoff + m * 2048 + k * 1024); } while (0)
; #define PG8_MMA(ai, bj, At, Bt) do { __builtin_amdgcn_s_setprio(1); _Pragma("unroll") for (int m = 0; m < 4; ++m) _Pragma("unroll") for (int n = 0; n < 2; ++n) _Pragma("unroll") for (int k = 0; k < 2; ++k) \
;         acc[ai][bj][m][n] = __builtin_amdgcn_mfma_f32_16x16x32_bf16(Bt[n][k], At[m][k], acc[ai][bj][m][n], 0, 0, 0); __builtin_amdgcn_s_setprio(0); } while (0)
; #define PG8_WAIT_V(n) asm volatile("s_waitcnt vmcnt(" #n ")" ::: "memory")
; #define PG8_WAIT_L(n) asm volatile("s_waitcnt lgkmcnt(" #n ")" ::: "memory")
; #define PG8_BAR __builtin_amdgcn_s_barrier()
; #define PG8_SCHED __builtin_amdgcn_sched_barrier(0)
;     __device__ __forceinline__ void operator()(const f32x4 (&acc)[2][2][4][2], const Unit& u, int wr, int wc, int fr, int fq) const {
;         if (u.pn < 11) {
; template <class Epi>
; __device__ __forceinline__ void gemm_phase(LAS unsigned char* lds, const Gemm g, const int G, const int cidx, const Epi& E) {
;     ...
;             PG8_LDA(At, 1, 1); PG8_STAGE(PG8_SB(1, 0), b3, voffB); PG8_STAGE(PG8_SB(1, 1), b3 + hstep, voffB); PG8_STAGE(PG8_SA(1, 0), a3, voffA);
;             PG8_WAIT_V(8); PG8_WAIT_L(0); PG8_BAR; PG8_MMA(1, 0, At, B0); PG8_MMA(1, 1, At, B1); PG8_BAR; PG8_SCHED;
;         }
;         if constexpr (!Epi::AFTER_DRAIN) E(acc, cur, wr, wc, fr, fq);
	s_add_i32 s26, s43, s95
	v_lshl_add_u64 v[132:133], v[132:133], 0, s[46:47]
	s_mov_b32 m0, s26
	ds_read_b128 v[192:195], v163 offset:49152
	ds_read_b128 v[196:199], v163 offset:50176
	ds_read_b128 v[214:217], v163 offset:51200
	ds_read_b128 v[218:221], v163 offset:52224
	ds_read_b128 v[222:225], v163 offset:53248
	ds_read_b128 v[226:229], v163 offset:54272
	ds_read_b128 v[230:233], v163 offset:55296
	ds_read_b128 v[234:237], v163 offset:56320
	global_load_lds_dwordx4 v[132:133], off
	s_add_i32 m0, s26, 0x2000
	s_add_u32 s24, s24, 0x40080
	v_lshl_add_u64 v[132:133], v[134:135], 0, s[46:47]
	s_addc_u32 s25, s25, 0
	s_add_i32 s26, s68, s95
	global_load_lds_dwordx4 v[132:133], off
	v_lshl_add_u64 v[132:133], s[24:25], 0, v[148:149]
	s_mov_b32 m0, s26
	s_nop 0
	global_load_lds_dwordx4 v[132:133], off
	v_lshl_add_u64 v[132:133], s[24:25], 0, v[0:1]
	s_add_i32 m0, s26, 0x2000
	s_nop 0
	global_load_lds_dwordx4 v[132:133], off
	v_lshl_add_u64 v[132:133], v[140:141], 0, s[46:47]
	s_mov_b32 m0, s84
	s_nop 0
	global_load_lds_dwordx4 v[132:133], off
	v_lshl_add_u64 v[132:133], v[142:143], 0, s[46:47]
	s_mov_b32 m0, s76
	s_nop 0
	global_load_lds_dwordx4 v[132:133], off
	s_waitcnt vmcnt(8)
	s_waitcnt lgkmcnt(0)
	s_barrier
	s_waitcnt lgkmcnt(0)
	v_mfma_f32_16x16x32_bf16 v[64:67], v[158:161], v[192:195], v[64:67]
	v_mfma_f32_16x16x32_bf16 v[60:63], v[168:171], v[192:195], v[60:63]
	v_mfma_f32_16x16x32_bf16 v[56:59], v[158:161], v[214:217], v[56:59]
	v_mfma_f32_16x16x32_bf16 v[48:51], v[168:171], v[214:217], v[48:51]
	v_mfma_f32_16x16x32_bf16 v[40:43], v[158:161], v[222:225], v[40:43]
	v_mfma_f32_16x16x32_bf16 v[32:35], v[168:171], v[222:225], v[32:35]
	v_mfma_f32_16x16x32_bf16 v[24:27], v[158:161], v[230:233], v[24:27]
	v_mfma_f32_16x16x32_bf16 v[16:19], v[168:171], v[230:233], v[16:19]
	v_mfma_f32_16x16x32_bf16 v[64:67], v[164:167], v[196:199], v[64:67]
	v_mfma_f32_16x16x32_bf16 v[60:63], v[172:175], v[196:199], v[60:63]
	v_mfma_f32_16x16x32_bf16 v[56:59], v[164:167], v[218:221], v[56:59]
	v_mfma_f32_16x16x32_bf16 v[48:51], v[172:175], v[218:221], v[48:51]
	v_mfma_f32_16x16x32_bf16 v[40:43], v[164:167], v[226:229], v[40:43]
	v_mfma_f32_16x16x32_bf16 v[32:35], v[172:175], v[226:229], v[32:35]
	v_mfma_f32_16x16x32_bf16 v[24:27], v[164:167], v[234:237], v[24:27]
	v_mfma_f32_16x16x32_bf16 v[16:19], v[172:175], v[234:237], v[16:19]
	v_mfma_f32_16x16x32_bf16 v[52:55], v[176:179], v[192:195], v[52:55]
	v_mfma_f32_16x16x32_bf16 v[44:47], v[184:187], v[192:195], v[44:47]
	v_mfma_f32_16x16x32_bf16 v[36:39], v[176:179], v[214:217], v[36:39]
	v_mfma_f32_16x16x32_bf16 v[28:31], v[184:187], v[214:217], v[28:31]
	v_mfma_f32_16x16x32_bf16 v[20:23], v[176:179], v[222:225], v[20:23]
	v_mfma_f32_16x16x32_bf16 v[12:15], v[184:187], v[222:225], v[12:15]
	v_mfma_f32_16x16x32_bf16 v[8:11], v[176:179], v[230:233], v[8:11]
	v_mfma_f32_16x16x32_bf16 v[4:7], v[184:187], v[230:233], v[4:7]
	v_mfma_f32_16x16x32_bf16 v[52:55], v[180:183], v[196:199], v[52:55]
	v_mfma_f32_16x16x32_bf16 v[44:47], v[188:191], v[196:199], v[44:47]
	v_mfma_f32_16x16x32_bf16 v[36:39], v[180:183], v[218:221], v[36:39]
	v_mfma_f32_16x16x32_bf16 v[28:31], v[188:191], v[218:221], v[28:31]
	v_mfma_f32_16x16x32_bf16 v[20:23], v[180:183], v[226:229], v[20:23]
	v_mfma_f32_16x16x32_bf16 v[12:15], v[188:191], v[226:229], v[12:15]
	v_mfma_f32_16x16x32_bf16 v[8:11], v[180:183], v[234:237], v[8:11]
	v_mfma_f32_16x16x32_bf16 v[4:7], v[188:191], v[234:237], v[4:7]
	s_add_i32 s45, s45, 2
	s_add_u32 s42, s42, 0x100
	s_addc_u32 s44, s44, 0
	s_add_u32 s20, s20, 0x100
	s_addc_u32 s21, s21, 0
	s_cmp_gt_u32 s45, 13
	s_barrier
	s_cbranch_scc0 .LBB0_601
	s_cmp_gt_i32 s35, 10
	s_mov_b64 s[20:21], -1
	s_mov_b32 s26, 0x1a000
	s_mov_b32 s27, 0x19000
	s_cbranch_scc0 .LBB0_604
; __device__ __forceinline__ unsigned pk2(float lo, float hi) { unsigned r; asm("v_cvt_pk_bf16_f32 %0, %1, %2" : "=v"(r) : "v"(lo), "v"(hi)); return r; }
;     __device__ __forceinline__ void operator()(const f32x4 (&acc)[2][2][4][2], const Unit& u, int wr, int wc, int fr, int fq) const {
;     ...
;             const int g = u.pn - 11, n = g >> 2, q = g & 3;
;             bf16_t* blk = Gt + (((size_t)n * 64 + u.pm) * 8 + q * 2) * 32768 + (size_t)((wr * 4 * 4 + wc) * 64 + fq * 16 + fr) * 8;
; #pragma unroll
;             for (int ai = 0; ai < 2; ++ai)
; #pragma unroll
;                 for (int m = 0; m < 4; ++m)
; #pragma unroll
;                     for (int bj = 0; bj < 2; ++bj) { const f32x4 v0 = acc[ai][bj][m][0], v1 = acc[ai][bj][m][1];
;                         u32x4 w; w.x = pk2(v0[0], v0[1]); w.y = pk2(v0[2], v0[3]); w.z = pk2(v1[0], v1[1]); w.w = pk2(v1[2], v1[3]);
;                         *(u32x4*)(blk + (size_t)bj * 32768 + (size_t)((ai * 8 + m) * 4) * 512) = w; }
;         }
	s_add_i32 s9, s35, -11
	s_mov_b32 s21, s77
	s_lshr_b32 s20, s9, 2
	s_ashr_i32 s19, s18, 31
	s_lshl_b64 s[20:21], s[20:21], 9
	s_lshl_b64 s[24:25], s[18:19], 3
	s_add_u32 s11, s20, s24
	s_addc_u32 s21, s21, s25
	s_lshl_b32 s9, s9, 1
	s_and_b32 s9, s9, 6
	s_or_b32 s20, s11, s9
	s_lshl_b64 s[20:21], s[20:21], 16
	v_lshl_add_u64 v[158:159], v[152:153], 0, s[20:21]
	s_mov_b32 s9, 0x11000
	v_add_co_u32_e32 v132, vcc, s9, v158
	v_cvt_pk_bf16_f32 v164, v128, v129
	v_cvt_pk_bf16_f32 v165, v130, v131
	v_cvt_pk_bf16_f32 v166, v124, v125
	v_cvt_pk_bf16_f32 v167, v126, v127
	s_nop 1
	v_addc_co_u32_e32 v133, vcc, 0, v159, vcc
	global_store_dwordx4 v[158:159], v[164:167], off
	v_add_co_u32_e32 v134, vcc, s81, v158
	s_nop 0
	v_cvt_pk_bf16_f32 v164, v116, v117
	v_cvt_pk_bf16_f32 v165, v118, v119
	v_cvt_pk_bf16_f32 v166, v108, v109
	v_cvt_pk_bf16_f32 v167, v110, v111
	global_store_dwordx4 v[132:133], v[164:167], off offset:-4096
	v_addc_co_u32_e32 v135, vcc, 0, v159, vcc
	s_nop 0
	v_cvt_pk_bf16_f32 v164, v120, v121
	v_cvt_pk_bf16_f32 v165, v122, v123
	v_cvt_pk_bf16_f32 v166, v112, v113
	v_cvt_pk_bf16_f32 v167, v114, v115
	s_mov_b32 s9, 0x13000
	global_store_dwordx4 v[134:135], v[164:167], off offset:-4096
	s_mov_b64 s[20:21], 0
	s_nop 0
	v_cvt_pk_bf16_f32 v164, v100, v101
	v_cvt_pk_bf16_f32 v165, v102, v103
	v_cvt_pk_bf16_f32 v166, v92, v93
	v_cvt_pk_bf16_f32 v167, v94, v95
	global_store_dwordx4 v[132:133], v[164:167], off
	v_add_co_u32_e32 v132, vcc, s9, v158
	s_nop 0
	v_cvt_pk_bf16_f32 v164, v104, v105
	v_cvt_pk_bf16_f32 v165, v106, v107
	v_cvt_pk_bf16_f32 v166, v96, v97
	v_cvt_pk_bf16_f32 v167, v98, v99
	s_nop 0
	v_addc_co_u32_e32 v133, vcc, 0, v159, vcc
	global_store_dwordx4 v[134:135], v[164:167], off
	v_add_co_u32_e32 v134, vcc, s82, v158
	s_nop 0
	v_cvt_pk_bf16_f32 v164, v84, v85
	v_cvt_pk_bf16_f32 v165, v86, v87
	v_cvt_pk_bf16_f32 v166, v76, v77
	v_cvt_pk_bf16_f32 v167, v78, v79
	global_store_dwordx4 v[132:133], v[164:167], off offset:-4096
	v_addc_co_u32_e32 v135, vcc, 0, v159, vcc
	s_nop 0
	v_cvt_pk_bf16_f32 v164, v88, v89
	v_cvt_pk_bf16_f32 v165, v90, v91
	v_cvt_pk_bf16_f32 v166, v80, v81
	v_cvt_pk_bf16_f32 v167, v82, v83
	s_mov_b32 s9, 0x9000
	global_store_dwordx4 v[134:135], v[164:167], off
	s_nop 1
	v_cvt_pk_bf16_f32 v164, v72, v73
	v_cvt_pk_bf16_f32 v165, v74, v75
	v_cvt_pk_bf16_f32 v166, v68, v69
	v_cvt_pk_bf16_f32 v167, v70, v71
	global_store_dwordx4 v[132:133], v[164:167], off
	v_add_co_u32_e32 v132, vcc, s9, v158
	s_nop 0
	v_cvt_pk_bf16_f32 v164, v64, v65
	v_cvt_pk_bf16_f32 v165, v66, v67
	v_cvt_pk_bf16_f32 v166, v60, v61
	v_cvt_pk_bf16_f32 v167, v62, v63
	s_nop 0
	v_addc_co_u32_e32 v133, vcc, 0, v159, vcc
	v_add_co_u32_e32 v134, vcc, s27, v158
	global_store_dwordx4 v[132:133], v[164:167], off offset:-4096
	s_nop 0
	v_addc_co_u32_e32 v135, vcc, 0, v159, vcc
	v_cvt_pk_bf16_f32 v164, v52, v53
	v_cvt_pk_bf16_f32 v165, v54, v55
	v_cvt_pk_bf16_f32 v166, v44, v45
	v_cvt_pk_bf16_f32 v167, v46, v47
	s_mov_b32 s9, 0xb000
	global_store_dwordx4 v[134:135], v[164:167], off offset:-4096
	s_nop 1
	v_cvt_pk_bf16_f32 v164, v56, v57
	v_cvt_pk_bf16_f32 v165, v58, v59
	v_cvt_pk_bf16_f32 v166, v48, v49
	v_cvt_pk_bf16_f32 v167, v50, v51
	global_store_dwordx4 v[132:133], v[164:167], off
	v_add_co_u32_e32 v132, vcc, s9, v158
	s_nop 0
	v_cvt_pk_bf16_f32 v164, v36, v37
	v_cvt_pk_bf16_f32 v165, v38, v39
	v_cvt_pk_bf16_f32 v166, v28, v29
	v_cvt_pk_bf16_f32 v167, v30, v31
	s_nop 0
	v_addc_co_u32_e32 v133, vcc, 0, v159, vcc
	global_store_dwordx4 v[134:135], v[164:167], off
	v_add_co_u32_e32 v134, vcc, s26, v158
	s_nop 0
	v_cvt_pk_bf16_f32 v164, v40, v41
	v_cvt_pk_bf16_f32 v165, v42, v43
	v_cvt_pk_bf16_f32 v166, v32, v33
	v_cvt_pk_bf16_f32 v167, v34, v35
	global_store_dwordx4 v[132:133], v[164:167], off offset:-4096
	v_addc_co_u32_e32 v135, vcc, 0, v159, vcc
	s_nop 0
	v_cvt_pk_bf16_f32 v164, v20, v21
	v_cvt_pk_bf16_f32 v165, v22, v23
	v_cvt_pk_bf16_f32 v166, v12, v13
	v_cvt_pk_bf16_f32 v167, v14, v15
	global_store_dwordx4 v[134:135], v[164:167], off
	s_nop 1
	v_cvt_pk_bf16_f32 v164, v24, v25
	v_cvt_pk_bf16_f32 v165, v26, v27
	v_cvt_pk_bf16_f32 v166, v16, v17
	v_cvt_pk_bf16_f32 v167, v18, v19
	global_store_dwordx4 v[132:133], v[164:167], off
	v_add_co_u32_e32 v132, vcc, 0x1b000, v158
	s_nop 0
	v_cvt_pk_bf16_f32 v164, v8, v9
	v_cvt_pk_bf16_f32 v165, v10, v11
	v_cvt_pk_bf16_f32 v166, v4, v5
	v_cvt_pk_bf16_f32 v167, v6, v7
	s_nop 0
	v_addc_co_u32_e32 v133, vcc, 0, v159, vcc
	global_store_dwordx4 v[132:133], v[164:167], off
